# scan: per-chunk global loads four chunks ahead (chunk loop unrolled x4, four load register sets)
# speedup vs baseline: 1.0074x; 1.0074x over previous
.LBB0_1063:
	s_andn2_b64 vcc, exec, s[0:1]
	s_cbranch_vccnz .LBB0_1071
	v_readlane_b32 s0, v207, 5
	v_readlane_b32 s1, v207, 6
	s_and_b64 s[0:1], s[0:1], exec
	v_readlane_b32 s0, v208, 26
	s_cselect_b32 s0, s0, s97
	s_and_b32 s7, s0, 3
	s_lshr_b32 s6, s0, 2
	s_lshr_b32 s9, s0, 5
	s_lshl_b32 s2, s6, 5
	s_and_b32 s2, s2, 0xc0
	s_and_b32 s3, s6, 1
	v_readlane_b32 s4, v210, 50
	v_readlane_b32 s5, v210, 51
	v_readlane_b32 s52, v210, 32
	v_readlane_b32 s53, v210, 33
	v_readlane_b32 s8, v208, 60
	s_cmp_eq_u32 s3, 0
	s_cselect_b32 s46, s14, s16
	s_cselect_b32 s47, s15, s17
	s_cselect_b32 s48, s18, s20
	s_cselect_b32 s49, s19, s21
	s_cselect_b32 s50, s26, s4
	s_cselect_b32 s51, s27, s5
	s_cselect_b32 s34, 16, -16
	s_cselect_b32 s10, 1, -1
	s_cselect_b32 s54, 0, 0xff
	s_cselect_b32 s55, 0, 0xfff
	s_lshl_b32 s0, s9, 8
	s_add_i32 s0, s0, 0x4000
	s_add_i32 s54, s54, s0
	s_lshl_b32 s0, s9, 12
	s_add_i32 s55, s55, s0
	s_setprio 3
	v_lshrrev_b32_e32 v119, 4, v133
	v_and_b32_e32 v120, 15, v133
	v_and_b32_e32 v121, 12, v120
	v_and_b32_e32 v0, 1, v120
	v_lshl_or_b32 v121, v0, 1, v121
	v_bfe_u32 v0, v120, 1, 1
	v_or_b32_e32 v121, v121, v0
	v_mul_i32_i24_e32 v0, s10, v119
	v_add_u32_e32 v113, s54, v0
	v_add_u32_e32 v117, s55, v0
	v_mul_i32_i24_e32 v0, s10, v121
	v_add_u32_e32 v114, s54, v0
	v_add_u32_e32 v126, s55, v0
	v_and_b32_e32 v0, 8, v120
	v_cmp_ne_u32_e64 s[38:39], 0, v0
	v_and_b32_e32 v0, 4, v120
	v_cmp_ne_u32_e64 s[40:41], 0, v0
	v_and_b32_e32 v0, 1, v120
	v_cmp_ne_u32_e64 s[42:43], 0, v0
	v_and_b32_e32 v0, 2, v120
	v_cmp_ne_u32_e64 s[44:45], 0, v0
	v_lshlrev_b32_e32 v0, 4, v120
	s_lshl_b32 s0, s2, 2
	v_add_u32_e32 v115, s0, v0
	s_lshl_b32 s1, s7, 4
	v_add_u32_e32 v122, s1, v119
	v_lshl_add_u32 v116, v122, 2, s0
	v_mov_b32_e32 v110, v0
	v_lshlrev_b32_e32 v111, 2, v122
	v_lshl_add_u32 v112, v119, 8, v0
	s_lshl_b32 s8, s8, 10
	s_add_u32 s52, s52, s8
	s_addc_u32 s53, s53, 0
	global_load_dwordx4 v[6:9], v115, s[52:53]
	v_mov_b32_e32 v2, 0
	v_mov_b32_e32 v3, 0
	v_mov_b32_e32 v4, 0
	v_mov_b32_e32 v5, 0
	v_mov_b32_e32 v82, 0
	v_mov_b32_e32 v83, 0
	v_mov_b32_e32 v84, 0
	v_mov_b32_e32 v85, 0
	v_mov_b32_e32 v92, 0
	s_mov_b32 s33, 0
	v_mul_u32_u24_e32 v0, 0xf00, v113
	v_lshl_add_u32 v125, v113, 10, v115
	v_add_u32_e32 v0, v0, v115
	v_add_u32_e32 v113, s34, v113
	global_load_dwordx4 v[22:25], v125, s[46:47]
	global_load_dwordx4 v[26:29], v125, s[48:49]
	global_load_dwordx4 v[30:33], v125, s[22:23]
	global_load_dwordx4 v[14:17], v0, s[12:13] offset:1024
	global_load_dwordx4 v[10:13], v0, s[12:13]
	global_load_dwordx4 v[18:21], v0, s[12:13] offset:2048
	s_waitcnt vmcnt(0)
	v_pk_add_f32 v[122:123], v[26:27], -1.0 op_sel_hi:[1,0]
	v_pk_add_f32 v[124:125], v[28:29], -1.0 op_sel_hi:[1,0]
	v_pk_mul_f32 v[118:119], v[30:31], v[26:27]
	v_pk_fma_f32 v[122:123], v[6:7], v[122:123], 1.0 op_sel_hi:[1,1,0]
	v_pk_fma_f32 v[124:125], v[8:9], v[124:125], 1.0 op_sel_hi:[1,1,0]
	v_pk_mul_f32 v[120:121], v[32:33], v[28:29]
	v_pk_mul_f32 v[122:123], v[14:15], v[122:123]
	v_pk_mul_f32 v[124:125], v[16:17], v[124:125]
	ds_write_b128 v112, v[22:25] offset:0
	ds_write_b128 v112, v[30:33] offset:4096
	ds_write_b128 v112, v[10:13] offset:16384
	ds_write_b128 v112, v[18:21] offset:20480
	ds_write_b128 v112, v[118:121] offset:8192
	ds_write_b128 v112, v[122:125] offset:12288
	s_waitcnt lgkmcnt(0)
	v_xor_b32_e32 v112, 0x6000, v112
	v_mul_u32_u24_e32 v0, 0xf00, v113
	v_lshl_add_u32 v125, v113, 10, v115
	v_add_u32_e32 v0, v0, v115
	v_add_u32_e32 v113, s34, v113
	global_load_dwordx4 v[146:149], v125, s[46:47]
	global_load_dwordx4 v[150:153], v125, s[48:49]
	global_load_dwordx4 v[154:157], v125, s[22:23]
	global_load_dwordx4 v[138:141], v0, s[12:13] offset:1024
	global_load_dwordx4 v[134:137], v0, s[12:13]
	global_load_dwordx4 v[142:145], v0, s[12:13] offset:2048
	v_mul_u32_u24_e32 v0, 0xf00, v113
	v_lshl_add_u32 v125, v113, 10, v115
	v_add_u32_e32 v0, v0, v115
	v_add_u32_e32 v113, s34, v113
	global_load_dwordx4 v[194:197], v125, s[46:47]
	global_load_dwordx4 v[198:201], v125, s[48:49]
	global_load_dwordx4 v[202:205], v125, s[22:23]
	global_load_dwordx4 v[186:189], v0, s[12:13] offset:1024
	global_load_dwordx4 v[182:185], v0, s[12:13]
	global_load_dwordx4 v[190:193], v0, s[12:13] offset:2048
	v_mul_u32_u24_e32 v0, 0xf00, v113
	v_lshl_add_u32 v125, v113, 10, v115
	v_add_u32_e32 v0, v0, v115
	v_add_u32_e32 v113, s34, v113
	global_load_dwordx4 v[224:227], v125, s[46:47]
	global_load_dwordx4 v[228:231], v125, s[48:49]
	global_load_dwordx4 v[232:235], v125, s[22:23]
	global_load_dwordx4 v[216:219], v0, s[12:13] offset:1024
	global_load_dwordx4 v[212:215], v0, s[12:13]
	global_load_dwordx4 v[220:223], v0, s[12:13] offset:2048
	s_barrier
.Lscan_chunk:
	ds_read_b128 v[38:41], v110 offset:4096
	ds_read_b128 v[34:37], v110 offset:0
	ds_read_b128 v[46:49], v110 offset:12288
	ds_read_b32 v54, v111 offset:20480
	ds_read_b128 v[42:45], v110 offset:8192
	ds_read_b128 v[50:53], v110 offset:16384
	ds_read_b128 v[60:63], v110 offset:4352
	ds_read_b128 v[56:59], v110 offset:256
	ds_read_b128 v[68:71], v110 offset:12544
	ds_read_b32 v76, v111 offset:20736
	ds_read_b128 v[64:67], v110 offset:8448
	ds_read_b128 v[72:75], v110 offset:16640
	s_cmpk_ge_i32 s33, 0x10c
	s_cbranch_scc1 .Lscan_skipload_c0
	v_mul_u32_u24_e32 v0, 0xf00, v113
	v_lshl_add_u32 v125, v113, 10, v115
	v_add_u32_e32 v0, v0, v115
	v_add_u32_e32 v113, s34, v113
	global_load_dwordx4 v[22:25], v125, s[46:47]
	global_load_dwordx4 v[26:29], v125, s[48:49]
	global_load_dwordx4 v[30:33], v125, s[22:23]
	global_load_dwordx4 v[14:17], v0, s[12:13] offset:1024
	global_load_dwordx4 v[10:13], v0, s[12:13]
	global_load_dwordx4 v[18:21], v0, s[12:13] offset:2048
	s_cmp_eq_u32 s33, 11
	s_cbranch_scc0 .Lscan_nogload_c0
	v_mov_b32_e32 v113, v117
	s_branch .Lscan_nogload_c0

.Lscan_nored_c0:
	s_waitcnt lgkmcnt(1)
	v_pk_mul_f32 v[86:87], v[2:3], v[38:39]
	v_pk_mul_f32 v[78:79], v[2:3], v[34:35]
	v_pk_fma_f32 v[86:87], v[4:5], v[40:41], v[86:87]
	v_pk_mul_f32 v[80:81], v[4:5], v[36:37]
	ds_read_b128 v[38:41], v110 offset:4608
	v_add_f32_e32 v90, v86, v87
	v_pk_fma_f32 v[82:83], v[54:55], v[46:47], v[78:79] op_sel_hi:[0,1,1]
	ds_read_b128 v[34:37], v110 offset:512
	v_add_f32_dpp v90, v90, v90 quad_perm:[1,0,3,2] row_mask:0xf bank_mask:0xf bound_ctrl:1
	v_pk_fma_f32 v[84:85], v[54:55], v[48:49], v[80:81] op_sel_hi:[0,1,1]
	ds_read_b128 v[46:49], v110 offset:12800
	v_add_f32_dpp v90, v90, v90 quad_perm:[2,3,0,1] row_mask:0xf bank_mask:0xf bound_ctrl:1
	ds_read_b32 v54, v111 offset:20992
	s_nop 0
	v_add_f32_dpp v90, v90, v90 row_half_mirror row_mask:0xf bank_mask:0xf bound_ctrl:1
	s_nop 0
	s_nop 0
	v_add_f32_dpp v92, v90, v90 row_mirror row_mask:0xf bank_mask:0xf bound_ctrl:1
	v_pk_fma_f32 v[2:3], v[92:93], v[42:43], v[82:83] op_sel_hi:[0,1,1] neg_lo:[1,0,0] neg_hi:[1,0,0]
	v_pk_fma_f32 v[4:5], v[92:93], v[44:45], v[84:85] op_sel_hi:[0,1,1] neg_lo:[1,0,0] neg_hi:[1,0,0]
	ds_read_b128 v[42:45], v110 offset:8704
	v_pk_mul_f32 v[86:87], v[2:3], v[60:61]
	v_pk_mul_f32 v[78:79], v[2:3], v[56:57]
	v_pk_fma_f32 v[86:87], v[4:5], v[62:63], v[86:87]
	v_pk_mul_f32 v[80:81], v[4:5], v[58:59]
	v_pk_mul_f32 v[88:89], v[2:3], v[50:51]
	v_add_f32_e32 v90, v86, v87
	v_pk_fma_f32 v[82:83], v[76:77], v[68:69], v[78:79] op_sel_hi:[0,1,1]
	v_pk_fma_f32 v[88:89], v[4:5], v[52:53], v[88:89]
	v_add_f32_dpp v90, v90, v90 quad_perm:[1,0,3,2] row_mask:0xf bank_mask:0xf bound_ctrl:1
	v_pk_fma_f32 v[84:85], v[76:77], v[70:71], v[80:81] op_sel_hi:[0,1,1]
	ds_read_b128 v[60:63], v110 offset:4864
	v_add_f32_dpp v90, v90, v90 quad_perm:[2,3,0,1] row_mask:0xf bank_mask:0xf bound_ctrl:1
	ds_read_b128 v[56:59], v110 offset:768
	v_add_f32_e32 v94, v88, v89
	v_add_f32_dpp v90, v90, v90 row_half_mirror row_mask:0xf bank_mask:0xf bound_ctrl:1
	ds_read_b128 v[50:53], v110 offset:16896
	ds_read_b128 v[68:71], v110 offset:13056
	v_add_f32_dpp v92, v90, v90 row_mirror row_mask:0xf bank_mask:0xf bound_ctrl:1
	ds_read_b32 v76, v111 offset:21248
	v_pk_fma_f32 v[2:3], v[92:93], v[64:65], v[82:83] op_sel_hi:[0,1,1] neg_lo:[1,0,0] neg_hi:[1,0,0]
	v_pk_fma_f32 v[4:5], v[92:93], v[66:67], v[84:85] op_sel_hi:[0,1,1] neg_lo:[1,0,0] neg_hi:[1,0,0]
	ds_read_b128 v[64:67], v110 offset:8960
	s_waitcnt lgkmcnt(6)
	v_pk_mul_f32 v[86:87], v[2:3], v[38:39]
	v_pk_mul_f32 v[78:79], v[2:3], v[34:35]
	v_pk_fma_f32 v[86:87], v[4:5], v[40:41], v[86:87]
	v_pk_mul_f32 v[80:81], v[4:5], v[36:37]
	v_pk_mul_f32 v[88:89], v[2:3], v[72:73]
	v_add_f32_e32 v90, v86, v87
	v_pk_fma_f32 v[82:83], v[54:55], v[46:47], v[78:79] op_sel_hi:[0,1,1]
	v_pk_fma_f32 v[88:89], v[4:5], v[74:75], v[88:89]
	v_add_f32_dpp v90, v90, v90 quad_perm:[1,0,3,2] row_mask:0xf bank_mask:0xf bound_ctrl:1
	v_pk_fma_f32 v[84:85], v[54:55], v[48:49], v[80:81] op_sel_hi:[0,1,1]
	ds_read_b128 v[38:41], v110 offset:5120
	v_add_f32_dpp v90, v90, v90 quad_perm:[2,3,0,1] row_mask:0xf bank_mask:0xf bound_ctrl:1
	ds_read_b128 v[34:37], v110 offset:1024
	v_add_f32_e32 v95, v88, v89
	v_add_f32_dpp v90, v90, v90 row_half_mirror row_mask:0xf bank_mask:0xf bound_ctrl:1
	ds_read_b128 v[72:75], v110 offset:17152
	ds_read_b128 v[46:49], v110 offset:13312
	v_add_f32_dpp v92, v90, v90 row_mirror row_mask:0xf bank_mask:0xf bound_ctrl:1
	ds_read_b32 v54, v111 offset:21504
	v_pk_fma_f32 v[2:3], v[92:93], v[42:43], v[82:83] op_sel_hi:[0,1,1] neg_lo:[1,0,0] neg_hi:[1,0,0]
	v_pk_fma_f32 v[4:5], v[92:93], v[44:45], v[84:85] op_sel_hi:[0,1,1] neg_lo:[1,0,0] neg_hi:[1,0,0]
	ds_read_b128 v[42:45], v110 offset:9216
	s_waitcnt lgkmcnt(6)
	v_pk_mul_f32 v[86:87], v[2:3], v[60:61]
	v_pk_mul_f32 v[78:79], v[2:3], v[56:57]
	v_pk_fma_f32 v[86:87], v[4:5], v[62:63], v[86:87]
	v_pk_mul_f32 v[80:81], v[4:5], v[58:59]
	v_pk_mul_f32 v[88:89], v[2:3], v[50:51]
	v_add_f32_e32 v90, v86, v87
	v_pk_fma_f32 v[82:83], v[76:77], v[68:69], v[78:79] op_sel_hi:[0,1,1]
	v_pk_fma_f32 v[88:89], v[4:5], v[52:53], v[88:89]
	v_add_f32_dpp v90, v90, v90 quad_perm:[1,0,3,2] row_mask:0xf bank_mask:0xf bound_ctrl:1
	v_pk_fma_f32 v[84:85], v[76:77], v[70:71], v[80:81] op_sel_hi:[0,1,1]
	ds_read_b128 v[60:63], v110 offset:5376
	v_add_f32_dpp v90, v90, v90 quad_perm:[2,3,0,1] row_mask:0xf bank_mask:0xf bound_ctrl:1
	ds_read_b128 v[56:59], v110 offset:1280
	v_add_f32_e32 v96, v88, v89
	v_add_f32_dpp v90, v90, v90 row_half_mirror row_mask:0xf bank_mask:0xf bound_ctrl:1
	ds_read_b128 v[50:53], v110 offset:17408
	ds_read_b128 v[68:71], v110 offset:13568
	v_add_f32_dpp v92, v90, v90 row_mirror row_mask:0xf bank_mask:0xf bound_ctrl:1
	ds_read_b32 v76, v111 offset:21760
	v_pk_fma_f32 v[2:3], v[92:93], v[64:65], v[82:83] op_sel_hi:[0,1,1] neg_lo:[1,0,0] neg_hi:[1,0,0]
	v_pk_fma_f32 v[4:5], v[92:93], v[66:67], v[84:85] op_sel_hi:[0,1,1] neg_lo:[1,0,0] neg_hi:[1,0,0]
	ds_read_b128 v[64:67], v110 offset:9472
	s_waitcnt lgkmcnt(6)
	v_pk_mul_f32 v[86:87], v[2:3], v[38:39]
	v_pk_mul_f32 v[78:79], v[2:3], v[34:35]
	v_pk_fma_f32 v[86:87], v[4:5], v[40:41], v[86:87]
	v_pk_mul_f32 v[80:81], v[4:5], v[36:37]
	v_pk_mul_f32 v[88:89], v[2:3], v[72:73]
	v_add_f32_e32 v90, v86, v87
	v_pk_fma_f32 v[82:83], v[54:55], v[46:47], v[78:79] op_sel_hi:[0,1,1]
	v_pk_fma_f32 v[88:89], v[4:5], v[74:75], v[88:89]
	v_add_f32_dpp v90, v90, v90 quad_perm:[1,0,3,2] row_mask:0xf bank_mask:0xf bound_ctrl:1
	v_pk_fma_f32 v[84:85], v[54:55], v[48:49], v[80:81] op_sel_hi:[0,1,1]
	ds_read_b128 v[38:41], v110 offset:5632
	v_add_f32_dpp v90, v90, v90 quad_perm:[2,3,0,1] row_mask:0xf bank_mask:0xf bound_ctrl:1
	ds_read_b128 v[34:37], v110 offset:1536
	v_add_f32_e32 v97, v88, v89
	v_add_f32_dpp v90, v90, v90 row_half_mirror row_mask:0xf bank_mask:0xf bound_ctrl:1
	ds_read_b128 v[72:75], v110 offset:17664
	ds_read_b128 v[46:49], v110 offset:13824
	v_add_f32_dpp v92, v90, v90 row_mirror row_mask:0xf bank_mask:0xf bound_ctrl:1
	ds_read_b32 v54, v111 offset:22016
	v_pk_fma_f32 v[2:3], v[92:93], v[42:43], v[82:83] op_sel_hi:[0,1,1] neg_lo:[1,0,0] neg_hi:[1,0,0]
	v_pk_fma_f32 v[4:5], v[92:93], v[44:45], v[84:85] op_sel_hi:[0,1,1] neg_lo:[1,0,0] neg_hi:[1,0,0]
	ds_read_b128 v[42:45], v110 offset:9728
	s_waitcnt lgkmcnt(6)
	v_pk_mul_f32 v[86:87], v[2:3], v[60:61]
	v_pk_mul_f32 v[78:79], v[2:3], v[56:57]
	v_pk_fma_f32 v[86:87], v[4:5], v[62:63], v[86:87]
	v_pk_mul_f32 v[80:81], v[4:5], v[58:59]
	v_pk_mul_f32 v[88:89], v[2:3], v[50:51]
	v_add_f32_e32 v90, v86, v87
	v_pk_fma_f32 v[82:83], v[76:77], v[68:69], v[78:79] op_sel_hi:[0,1,1]
	v_pk_fma_f32 v[88:89], v[4:5], v[52:53], v[88:89]
	v_add_f32_dpp v90, v90, v90 quad_perm:[1,0,3,2] row_mask:0xf bank_mask:0xf bound_ctrl:1
	v_pk_fma_f32 v[84:85], v[76:77], v[70:71], v[80:81] op_sel_hi:[0,1,1]
	ds_read_b128 v[60:63], v110 offset:5888
	v_add_f32_dpp v90, v90, v90 quad_perm:[2,3,0,1] row_mask:0xf bank_mask:0xf bound_ctrl:1
	ds_read_b128 v[56:59], v110 offset:1792
	v_add_f32_e32 v98, v88, v89
	v_add_f32_dpp v90, v90, v90 row_half_mirror row_mask:0xf bank_mask:0xf bound_ctrl:1
	ds_read_b128 v[50:53], v110 offset:17920
	ds_read_b128 v[68:71], v110 offset:14080
	v_add_f32_dpp v92, v90, v90 row_mirror row_mask:0xf bank_mask:0xf bound_ctrl:1
	ds_read_b32 v76, v111 offset:22272
	v_pk_fma_f32 v[2:3], v[92:93], v[64:65], v[82:83] op_sel_hi:[0,1,1] neg_lo:[1,0,0] neg_hi:[1,0,0]
	v_pk_fma_f32 v[4:5], v[92:93], v[66:67], v[84:85] op_sel_hi:[0,1,1] neg_lo:[1,0,0] neg_hi:[1,0,0]
	ds_read_b128 v[64:67], v110 offset:9984
	s_waitcnt lgkmcnt(6)
	v_pk_mul_f32 v[86:87], v[2:3], v[38:39]
	v_pk_mul_f32 v[78:79], v[2:3], v[34:35]
	v_pk_fma_f32 v[86:87], v[4:5], v[40:41], v[86:87]
	v_pk_mul_f32 v[80:81], v[4:5], v[36:37]
	v_pk_mul_f32 v[88:89], v[2:3], v[72:73]
	v_add_f32_e32 v90, v86, v87
	v_pk_fma_f32 v[82:83], v[54:55], v[46:47], v[78:79] op_sel_hi:[0,1,1]
	v_pk_fma_f32 v[88:89], v[4:5], v[74:75], v[88:89]
	v_add_f32_dpp v90, v90, v90 quad_perm:[1,0,3,2] row_mask:0xf bank_mask:0xf bound_ctrl:1
	v_pk_fma_f32 v[84:85], v[54:55], v[48:49], v[80:81] op_sel_hi:[0,1,1]
	ds_read_b128 v[38:41], v110 offset:6144
	v_add_f32_dpp v90, v90, v90 quad_perm:[2,3,0,1] row_mask:0xf bank_mask:0xf bound_ctrl:1
	ds_read_b128 v[34:37], v110 offset:2048
	v_add_f32_e32 v99, v88, v89
	v_add_f32_dpp v90, v90, v90 row_half_mirror row_mask:0xf bank_mask:0xf bound_ctrl:1
	ds_read_b128 v[72:75], v110 offset:18176
	ds_read_b128 v[46:49], v110 offset:14336
	v_add_f32_dpp v92, v90, v90 row_mirror row_mask:0xf bank_mask:0xf bound_ctrl:1
	ds_read_b32 v54, v111 offset:22528
	v_pk_fma_f32 v[2:3], v[92:93], v[42:43], v[82:83] op_sel_hi:[0,1,1] neg_lo:[1,0,0] neg_hi:[1,0,0]
	v_pk_fma_f32 v[4:5], v[92:93], v[44:45], v[84:85] op_sel_hi:[0,1,1] neg_lo:[1,0,0] neg_hi:[1,0,0]
	ds_read_b128 v[42:45], v110 offset:10240
	s_waitcnt lgkmcnt(6)
	v_pk_mul_f32 v[86:87], v[2:3], v[60:61]
	v_pk_mul_f32 v[78:79], v[2:3], v[56:57]
	v_pk_fma_f32 v[86:87], v[4:5], v[62:63], v[86:87]
	v_pk_mul_f32 v[80:81], v[4:5], v[58:59]
	v_pk_mul_f32 v[88:89], v[2:3], v[50:51]
	v_add_f32_e32 v90, v86, v87
	v_pk_fma_f32 v[82:83], v[76:77], v[68:69], v[78:79] op_sel_hi:[0,1,1]
	v_pk_fma_f32 v[88:89], v[4:5], v[52:53], v[88:89]
	v_add_f32_dpp v90, v90, v90 quad_perm:[1,0,3,2] row_mask:0xf bank_mask:0xf bound_ctrl:1
	v_pk_fma_f32 v[84:85], v[76:77], v[70:71], v[80:81] op_sel_hi:[0,1,1]
	ds_read_b128 v[60:63], v110 offset:6400
	v_add_f32_dpp v90, v90, v90 quad_perm:[2,3,0,1] row_mask:0xf bank_mask:0xf bound_ctrl:1
	ds_read_b128 v[56:59], v110 offset:2304
	v_add_f32_e32 v100, v88, v89
	v_add_f32_dpp v90, v90, v90 row_half_mirror row_mask:0xf bank_mask:0xf bound_ctrl:1
	ds_read_b128 v[50:53], v110 offset:18432
	ds_read_b128 v[68:71], v110 offset:14592
	v_add_f32_dpp v92, v90, v90 row_mirror row_mask:0xf bank_mask:0xf bound_ctrl:1
	ds_read_b32 v76, v111 offset:22784
	v_pk_fma_f32 v[2:3], v[92:93], v[64:65], v[82:83] op_sel_hi:[0,1,1] neg_lo:[1,0,0] neg_hi:[1,0,0]
	v_pk_fma_f32 v[4:5], v[92:93], v[66:67], v[84:85] op_sel_hi:[0,1,1] neg_lo:[1,0,0] neg_hi:[1,0,0]
	ds_read_b128 v[64:67], v110 offset:10496
	s_waitcnt lgkmcnt(6)
	v_pk_mul_f32 v[86:87], v[2:3], v[38:39]
	v_pk_mul_f32 v[78:79], v[2:3], v[34:35]
	v_pk_fma_f32 v[86:87], v[4:5], v[40:41], v[86:87]
	v_pk_mul_f32 v[80:81], v[4:5], v[36:37]
	v_pk_mul_f32 v[88:89], v[2:3], v[72:73]
	v_add_f32_e32 v90, v86, v87
	v_pk_fma_f32 v[82:83], v[54:55], v[46:47], v[78:79] op_sel_hi:[0,1,1]
	v_pk_fma_f32 v[88:89], v[4:5], v[74:75], v[88:89]
	v_add_f32_dpp v90, v90, v90 quad_perm:[1,0,3,2] row_mask:0xf bank_mask:0xf bound_ctrl:1
	v_pk_fma_f32 v[84:85], v[54:55], v[48:49], v[80:81] op_sel_hi:[0,1,1]
	ds_read_b128 v[38:41], v110 offset:6656
	v_add_f32_dpp v90, v90, v90 quad_perm:[2,3,0,1] row_mask:0xf bank_mask:0xf bound_ctrl:1
	ds_read_b128 v[34:37], v110 offset:2560
	v_add_f32_e32 v101, v88, v89
	v_add_f32_dpp v90, v90, v90 row_half_mirror row_mask:0xf bank_mask:0xf bound_ctrl:1
	ds_read_b128 v[72:75], v110 offset:18688
	ds_read_b128 v[46:49], v110 offset:14848
	v_add_f32_dpp v92, v90, v90 row_mirror row_mask:0xf bank_mask:0xf bound_ctrl:1
	ds_read_b32 v54, v111 offset:23040
	v_pk_fma_f32 v[2:3], v[92:93], v[42:43], v[82:83] op_sel_hi:[0,1,1] neg_lo:[1,0,0] neg_hi:[1,0,0]
	v_pk_fma_f32 v[4:5], v[92:93], v[44:45], v[84:85] op_sel_hi:[0,1,1] neg_lo:[1,0,0] neg_hi:[1,0,0]
	ds_read_b128 v[42:45], v110 offset:10752
	s_waitcnt lgkmcnt(6)
	v_pk_mul_f32 v[86:87], v[2:3], v[60:61]
	v_pk_mul_f32 v[78:79], v[2:3], v[56:57]
	v_pk_fma_f32 v[86:87], v[4:5], v[62:63], v[86:87]
	v_pk_mul_f32 v[80:81], v[4:5], v[58:59]
	v_pk_mul_f32 v[88:89], v[2:3], v[50:51]
	v_add_f32_e32 v90, v86, v87
	v_pk_fma_f32 v[82:83], v[76:77], v[68:69], v[78:79] op_sel_hi:[0,1,1]
	v_pk_fma_f32 v[88:89], v[4:5], v[52:53], v[88:89]
	v_add_f32_dpp v90, v90, v90 quad_perm:[1,0,3,2] row_mask:0xf bank_mask:0xf bound_ctrl:1
	v_pk_fma_f32 v[84:85], v[76:77], v[70:71], v[80:81] op_sel_hi:[0,1,1]
	ds_read_b128 v[60:63], v110 offset:6912
	v_add_f32_dpp v90, v90, v90 quad_perm:[2,3,0,1] row_mask:0xf bank_mask:0xf bound_ctrl:1
	ds_read_b128 v[56:59], v110 offset:2816
	v_add_f32_e32 v102, v88, v89
	v_add_f32_dpp v90, v90, v90 row_half_mirror row_mask:0xf bank_mask:0xf bound_ctrl:1
	ds_read_b128 v[50:53], v110 offset:18944
	ds_read_b128 v[68:71], v110 offset:15104
	v_add_f32_dpp v92, v90, v90 row_mirror row_mask:0xf bank_mask:0xf bound_ctrl:1
	ds_read_b32 v76, v111 offset:23296
	v_pk_fma_f32 v[2:3], v[92:93], v[64:65], v[82:83] op_sel_hi:[0,1,1] neg_lo:[1,0,0] neg_hi:[1,0,0]
	v_pk_fma_f32 v[4:5], v[92:93], v[66:67], v[84:85] op_sel_hi:[0,1,1] neg_lo:[1,0,0] neg_hi:[1,0,0]
	ds_read_b128 v[64:67], v110 offset:11008
	s_waitcnt lgkmcnt(6)
	v_pk_mul_f32 v[86:87], v[2:3], v[38:39]
	v_pk_mul_f32 v[78:79], v[2:3], v[34:35]
	v_pk_fma_f32 v[86:87], v[4:5], v[40:41], v[86:87]
	v_pk_mul_f32 v[80:81], v[4:5], v[36:37]
	v_pk_mul_f32 v[88:89], v[2:3], v[72:73]
	v_add_f32_e32 v90, v86, v87
	v_pk_fma_f32 v[82:83], v[54:55], v[46:47], v[78:79] op_sel_hi:[0,1,1]
	v_pk_fma_f32 v[88:89], v[4:5], v[74:75], v[88:89]
	v_add_f32_dpp v90, v90, v90 quad_perm:[1,0,3,2] row_mask:0xf bank_mask:0xf bound_ctrl:1
	v_pk_fma_f32 v[84:85], v[54:55], v[48:49], v[80:81] op_sel_hi:[0,1,1]
	ds_read_b128 v[38:41], v110 offset:7168
	v_add_f32_dpp v90, v90, v90 quad_perm:[2,3,0,1] row_mask:0xf bank_mask:0xf bound_ctrl:1
	ds_read_b128 v[34:37], v110 offset:3072
	v_add_f32_e32 v103, v88, v89
	v_add_f32_dpp v90, v90, v90 row_half_mirror row_mask:0xf bank_mask:0xf bound_ctrl:1
	ds_read_b128 v[72:75], v110 offset:19200
	ds_read_b128 v[46:49], v110 offset:15360
	v_add_f32_dpp v92, v90, v90 row_mirror row_mask:0xf bank_mask:0xf bound_ctrl:1
	ds_read_b32 v54, v111 offset:23552
	v_pk_fma_f32 v[2:3], v[92:93], v[42:43], v[82:83] op_sel_hi:[0,1,1] neg_lo:[1,0,0] neg_hi:[1,0,0]
	v_pk_fma_f32 v[4:5], v[92:93], v[44:45], v[84:85] op_sel_hi:[0,1,1] neg_lo:[1,0,0] neg_hi:[1,0,0]
	ds_read_b128 v[42:45], v110 offset:11264
	s_waitcnt lgkmcnt(6)
	v_pk_mul_f32 v[86:87], v[2:3], v[60:61]
	v_pk_mul_f32 v[78:79], v[2:3], v[56:57]
	v_pk_fma_f32 v[86:87], v[4:5], v[62:63], v[86:87]
	v_pk_mul_f32 v[80:81], v[4:5], v[58:59]
	v_pk_mul_f32 v[88:89], v[2:3], v[50:51]
	v_add_f32_e32 v90, v86, v87
	v_pk_fma_f32 v[82:83], v[76:77], v[68:69], v[78:79] op_sel_hi:[0,1,1]
	v_pk_fma_f32 v[88:89], v[4:5], v[52:53], v[88:89]
	v_add_f32_dpp v90, v90, v90 quad_perm:[1,0,3,2] row_mask:0xf bank_mask:0xf bound_ctrl:1
	v_pk_fma_f32 v[84:85], v[76:77], v[70:71], v[80:81] op_sel_hi:[0,1,1]
	ds_read_b128 v[60:63], v110 offset:7424
	v_add_f32_dpp v90, v90, v90 quad_perm:[2,3,0,1] row_mask:0xf bank_mask:0xf bound_ctrl:1
	ds_read_b128 v[56:59], v110 offset:3328
	v_add_f32_e32 v104, v88, v89
	v_add_f32_dpp v90, v90, v90 row_half_mirror row_mask:0xf bank_mask:0xf bound_ctrl:1
	ds_read_b128 v[50:53], v110 offset:19456
	ds_read_b128 v[68:71], v110 offset:15616
	v_add_f32_dpp v92, v90, v90 row_mirror row_mask:0xf bank_mask:0xf bound_ctrl:1
	ds_read_b32 v76, v111 offset:23808
	v_pk_fma_f32 v[2:3], v[92:93], v[64:65], v[82:83] op_sel_hi:[0,1,1] neg_lo:[1,0,0] neg_hi:[1,0,0]
	v_pk_fma_f32 v[4:5], v[92:93], v[66:67], v[84:85] op_sel_hi:[0,1,1] neg_lo:[1,0,0] neg_hi:[1,0,0]
	ds_read_b128 v[64:67], v110 offset:11520
	s_waitcnt lgkmcnt(6)
	v_pk_mul_f32 v[86:87], v[2:3], v[38:39]
	v_pk_mul_f32 v[78:79], v[2:3], v[34:35]
	v_pk_fma_f32 v[86:87], v[4:5], v[40:41], v[86:87]
	v_pk_mul_f32 v[80:81], v[4:5], v[36:37]
	v_pk_mul_f32 v[88:89], v[2:3], v[72:73]
	v_add_f32_e32 v90, v86, v87
	v_pk_fma_f32 v[82:83], v[54:55], v[46:47], v[78:79] op_sel_hi:[0,1,1]
	v_pk_fma_f32 v[88:89], v[4:5], v[74:75], v[88:89]
	v_add_f32_dpp v90, v90, v90 quad_perm:[1,0,3,2] row_mask:0xf bank_mask:0xf bound_ctrl:1
	v_pk_fma_f32 v[84:85], v[54:55], v[48:49], v[80:81] op_sel_hi:[0,1,1]
	ds_read_b128 v[38:41], v110 offset:7680
	v_add_f32_dpp v90, v90, v90 quad_perm:[2,3,0,1] row_mask:0xf bank_mask:0xf bound_ctrl:1
	ds_read_b128 v[34:37], v110 offset:3584
	v_add_f32_e32 v105, v88, v89
	v_add_f32_dpp v90, v90, v90 row_half_mirror row_mask:0xf bank_mask:0xf bound_ctrl:1
	ds_read_b128 v[72:75], v110 offset:19712
	ds_read_b128 v[46:49], v110 offset:15872
	v_add_f32_dpp v92, v90, v90 row_mirror row_mask:0xf bank_mask:0xf bound_ctrl:1
	ds_read_b32 v54, v111 offset:24064
	v_pk_fma_f32 v[2:3], v[92:93], v[42:43], v[82:83] op_sel_hi:[0,1,1] neg_lo:[1,0,0] neg_hi:[1,0,0]
	v_pk_fma_f32 v[4:5], v[92:93], v[44:45], v[84:85] op_sel_hi:[0,1,1] neg_lo:[1,0,0] neg_hi:[1,0,0]
	ds_read_b128 v[42:45], v110 offset:11776
	s_waitcnt lgkmcnt(6)
	v_pk_mul_f32 v[86:87], v[2:3], v[60:61]
	v_pk_mul_f32 v[78:79], v[2:3], v[56:57]
	v_pk_fma_f32 v[86:87], v[4:5], v[62:63], v[86:87]
	v_pk_mul_f32 v[80:81], v[4:5], v[58:59]
	v_pk_mul_f32 v[88:89], v[2:3], v[50:51]
	v_add_f32_e32 v90, v86, v87
	v_pk_fma_f32 v[82:83], v[76:77], v[68:69], v[78:79] op_sel_hi:[0,1,1]
	v_pk_fma_f32 v[88:89], v[4:5], v[52:53], v[88:89]
	v_add_f32_dpp v90, v90, v90 quad_perm:[1,0,3,2] row_mask:0xf bank_mask:0xf bound_ctrl:1
	v_pk_fma_f32 v[84:85], v[76:77], v[70:71], v[80:81] op_sel_hi:[0,1,1]
	ds_read_b128 v[60:63], v110 offset:7936
	v_add_f32_dpp v90, v90, v90 quad_perm:[2,3,0,1] row_mask:0xf bank_mask:0xf bound_ctrl:1
	ds_read_b128 v[56:59], v110 offset:3840
	v_add_f32_e32 v106, v88, v89
	v_add_f32_dpp v90, v90, v90 row_half_mirror row_mask:0xf bank_mask:0xf bound_ctrl:1
	ds_read_b128 v[50:53], v110 offset:19968
	ds_read_b128 v[68:71], v110 offset:16128
	v_add_f32_dpp v92, v90, v90 row_mirror row_mask:0xf bank_mask:0xf bound_ctrl:1
	ds_read_b32 v76, v111 offset:24320
	s_cmpk_eq_i32 s33, 0x10f
	s_cbranch_scc1 .Lscan_tail_last
	v_pk_fma_f32 v[2:3], v[92:93], v[64:65], v[82:83] op_sel_hi:[0,1,1] neg_lo:[1,0,0] neg_hi:[1,0,0]
	v_pk_fma_f32 v[4:5], v[92:93], v[66:67], v[84:85] op_sel_hi:[0,1,1] neg_lo:[1,0,0] neg_hi:[1,0,0]
	ds_read_b128 v[64:67], v110 offset:12032
	s_waitcnt lgkmcnt(6)
	v_pk_mul_f32 v[86:87], v[2:3], v[38:39]
	v_pk_mul_f32 v[78:79], v[2:3], v[34:35]
	v_pk_fma_f32 v[86:87], v[4:5], v[40:41], v[86:87]
	v_pk_mul_f32 v[80:81], v[4:5], v[36:37]
	v_pk_mul_f32 v[88:89], v[2:3], v[72:73]
	v_add_f32_e32 v90, v86, v87
	v_pk_fma_f32 v[82:83], v[54:55], v[46:47], v[78:79] op_sel_hi:[0,1,1]
	v_pk_fma_f32 v[88:89], v[4:5], v[74:75], v[88:89]
	v_add_f32_dpp v90, v90, v90 quad_perm:[1,0,3,2] row_mask:0xf bank_mask:0xf bound_ctrl:1
	v_pk_fma_f32 v[84:85], v[54:55], v[48:49], v[80:81] op_sel_hi:[0,1,1]
	s_waitcnt vmcnt(18)
	v_add_f32_dpp v90, v90, v90 quad_perm:[2,3,0,1] row_mask:0xf bank_mask:0xf bound_ctrl:1
	v_pk_add_f32 v[122:123], v[150:151], -1.0 op_sel_hi:[1,0]
	v_add_f32_e32 v107, v88, v89
	v_add_f32_dpp v90, v90, v90 row_half_mirror row_mask:0xf bank_mask:0xf bound_ctrl:1
	ds_read_b128 v[72:75], v110 offset:20224
	v_pk_add_f32 v[124:125], v[152:153], -1.0 op_sel_hi:[1,0]
	v_add_f32_dpp v92, v90, v90 row_mirror row_mask:0xf bank_mask:0xf bound_ctrl:1
	v_pk_mul_f32 v[118:119], v[154:155], v[150:151]
	v_pk_fma_f32 v[2:3], v[92:93], v[42:43], v[82:83] op_sel_hi:[0,1,1] neg_lo:[1,0,0] neg_hi:[1,0,0]
	v_pk_fma_f32 v[4:5], v[92:93], v[44:45], v[84:85] op_sel_hi:[0,1,1] neg_lo:[1,0,0] neg_hi:[1,0,0]
	v_pk_fma_f32 v[122:123], v[6:7], v[122:123], 1.0 op_sel_hi:[1,1,0]
	s_waitcnt lgkmcnt(1)
	v_pk_mul_f32 v[86:87], v[2:3], v[60:61]
	v_pk_mul_f32 v[78:79], v[2:3], v[56:57]
	v_pk_fma_f32 v[86:87], v[4:5], v[62:63], v[86:87]
	v_pk_mul_f32 v[80:81], v[4:5], v[58:59]
	v_pk_mul_f32 v[88:89], v[2:3], v[50:51]
	v_add_f32_e32 v90, v86, v87
	v_pk_fma_f32 v[82:83], v[76:77], v[68:69], v[78:79] op_sel_hi:[0,1,1]
	v_pk_fma_f32 v[88:89], v[4:5], v[52:53], v[88:89]
	v_add_f32_dpp v90, v90, v90 quad_perm:[1,0,3,2] row_mask:0xf bank_mask:0xf bound_ctrl:1
	v_pk_fma_f32 v[84:85], v[76:77], v[70:71], v[80:81] op_sel_hi:[0,1,1]
	v_pk_fma_f32 v[124:125], v[8:9], v[124:125], 1.0 op_sel_hi:[1,1,0]
	v_add_f32_dpp v90, v90, v90 quad_perm:[2,3,0,1] row_mask:0xf bank_mask:0xf bound_ctrl:1
	v_pk_mul_f32 v[120:121], v[156:157], v[152:153]
	v_add_f32_e32 v108, v88, v89
	v_add_f32_dpp v90, v90, v90 row_half_mirror row_mask:0xf bank_mask:0xf bound_ctrl:1
	v_pk_mul_f32 v[122:123], v[138:139], v[122:123]
	v_pk_mul_f32 v[124:125], v[140:141], v[124:125]
	v_add_f32_dpp v92, v90, v90 row_mirror row_mask:0xf bank_mask:0xf bound_ctrl:1
	ds_write_b128 v112, v[146:149] offset:0
	ds_write_b128 v112, v[154:157] offset:4096
	v_pk_fma_f32 v[2:3], v[92:93], v[64:65], v[82:83] op_sel_hi:[0,1,1] neg_lo:[1,0,0] neg_hi:[1,0,0]
	v_pk_fma_f32 v[4:5], v[92:93], v[66:67], v[84:85] op_sel_hi:[0,1,1] neg_lo:[1,0,0] neg_hi:[1,0,0]
	ds_write_b128 v112, v[134:137] offset:16384
	s_waitcnt lgkmcnt(3)
	v_pk_mul_f32 v[88:89], v[2:3], v[72:73]
	ds_write_b128 v112, v[142:145] offset:20480
	v_pk_fma_f32 v[88:89], v[4:5], v[74:75], v[88:89]
	ds_write_b128 v112, v[118:121] offset:8192
	v_add_f32_e32 v109, v88, v89
	ds_write_b128 v112, v[122:125] offset:12288
	s_waitcnt lgkmcnt(0)
	v_xor_b32_e32 v110, 0x6000, v110
	v_xor_b32_e32 v111, 0x6000, v111
	v_xor_b32_e32 v112, 0x6000, v112
	s_add_i32 s33, s33, 1
	s_barrier
	ds_read_b128 v[38:41], v110 offset:4096
	ds_read_b128 v[34:37], v110 offset:0
	ds_read_b128 v[46:49], v110 offset:12288
	ds_read_b32 v54, v111 offset:20480
	ds_read_b128 v[42:45], v110 offset:8192
	ds_read_b128 v[50:53], v110 offset:16384
	ds_read_b128 v[60:63], v110 offset:4352
	ds_read_b128 v[56:59], v110 offset:256
	ds_read_b128 v[68:71], v110 offset:12544
	ds_read_b32 v76, v111 offset:20736
	ds_read_b128 v[64:67], v110 offset:8448
	ds_read_b128 v[72:75], v110 offset:16640
	s_cmpk_ge_i32 s33, 0x10c
	s_cbranch_scc1 .Lscan_skipload_c1
	v_mul_u32_u24_e32 v0, 0xf00, v113
	v_lshl_add_u32 v125, v113, 10, v115
	v_add_u32_e32 v0, v0, v115
	v_add_u32_e32 v113, s34, v113
	global_load_dwordx4 v[146:149], v125, s[46:47]
	global_load_dwordx4 v[150:153], v125, s[48:49]
	global_load_dwordx4 v[154:157], v125, s[22:23]
	global_load_dwordx4 v[138:141], v0, s[12:13] offset:1024
	global_load_dwordx4 v[134:137], v0, s[12:13]
	global_load_dwordx4 v[142:145], v0, s[12:13] offset:2048
	s_cmp_eq_u32 s33, 11
	s_cbranch_scc0 .Lscan_nogload_c1
	v_mov_b32_e32 v113, v117
	s_branch .Lscan_nogload_c1

.Lscan_nored_c1:
	s_waitcnt lgkmcnt(1)
	v_pk_mul_f32 v[86:87], v[2:3], v[38:39]
	v_pk_mul_f32 v[78:79], v[2:3], v[34:35]
	v_pk_fma_f32 v[86:87], v[4:5], v[40:41], v[86:87]
	v_pk_mul_f32 v[80:81], v[4:5], v[36:37]
	ds_read_b128 v[38:41], v110 offset:4608
	v_add_f32_e32 v90, v86, v87
	v_pk_fma_f32 v[82:83], v[54:55], v[46:47], v[78:79] op_sel_hi:[0,1,1]
	ds_read_b128 v[34:37], v110 offset:512
	v_add_f32_dpp v90, v90, v90 quad_perm:[1,0,3,2] row_mask:0xf bank_mask:0xf bound_ctrl:1
	v_pk_fma_f32 v[84:85], v[54:55], v[48:49], v[80:81] op_sel_hi:[0,1,1]
	ds_read_b128 v[46:49], v110 offset:12800
	v_add_f32_dpp v90, v90, v90 quad_perm:[2,3,0,1] row_mask:0xf bank_mask:0xf bound_ctrl:1
	ds_read_b32 v54, v111 offset:20992
	s_nop 0
	v_add_f32_dpp v90, v90, v90 row_half_mirror row_mask:0xf bank_mask:0xf bound_ctrl:1
	s_nop 0
	s_nop 0
	v_add_f32_dpp v92, v90, v90 row_mirror row_mask:0xf bank_mask:0xf bound_ctrl:1
	v_pk_fma_f32 v[2:3], v[92:93], v[42:43], v[82:83] op_sel_hi:[0,1,1] neg_lo:[1,0,0] neg_hi:[1,0,0]
	v_pk_fma_f32 v[4:5], v[92:93], v[44:45], v[84:85] op_sel_hi:[0,1,1] neg_lo:[1,0,0] neg_hi:[1,0,0]
	ds_read_b128 v[42:45], v110 offset:8704
	v_pk_mul_f32 v[86:87], v[2:3], v[60:61]
	v_pk_mul_f32 v[78:79], v[2:3], v[56:57]
	v_pk_fma_f32 v[86:87], v[4:5], v[62:63], v[86:87]
	v_pk_mul_f32 v[80:81], v[4:5], v[58:59]
	v_pk_mul_f32 v[88:89], v[2:3], v[50:51]
	v_add_f32_e32 v90, v86, v87
	v_pk_fma_f32 v[82:83], v[76:77], v[68:69], v[78:79] op_sel_hi:[0,1,1]
	v_pk_fma_f32 v[88:89], v[4:5], v[52:53], v[88:89]
	v_add_f32_dpp v90, v90, v90 quad_perm:[1,0,3,2] row_mask:0xf bank_mask:0xf bound_ctrl:1
	v_pk_fma_f32 v[84:85], v[76:77], v[70:71], v[80:81] op_sel_hi:[0,1,1]
	ds_read_b128 v[60:63], v110 offset:4864
	v_add_f32_dpp v90, v90, v90 quad_perm:[2,3,0,1] row_mask:0xf bank_mask:0xf bound_ctrl:1
	ds_read_b128 v[56:59], v110 offset:768
	v_add_f32_e32 v94, v88, v89
	v_add_f32_dpp v90, v90, v90 row_half_mirror row_mask:0xf bank_mask:0xf bound_ctrl:1
	ds_read_b128 v[50:53], v110 offset:16896
	ds_read_b128 v[68:71], v110 offset:13056
	v_add_f32_dpp v92, v90, v90 row_mirror row_mask:0xf bank_mask:0xf bound_ctrl:1
	ds_read_b32 v76, v111 offset:21248
	v_pk_fma_f32 v[2:3], v[92:93], v[64:65], v[82:83] op_sel_hi:[0,1,1] neg_lo:[1,0,0] neg_hi:[1,0,0]
	v_pk_fma_f32 v[4:5], v[92:93], v[66:67], v[84:85] op_sel_hi:[0,1,1] neg_lo:[1,0,0] neg_hi:[1,0,0]
	ds_read_b128 v[64:67], v110 offset:8960
	s_waitcnt lgkmcnt(6)
	v_pk_mul_f32 v[86:87], v[2:3], v[38:39]
	v_pk_mul_f32 v[78:79], v[2:3], v[34:35]
	v_pk_fma_f32 v[86:87], v[4:5], v[40:41], v[86:87]
	v_pk_mul_f32 v[80:81], v[4:5], v[36:37]
	v_pk_mul_f32 v[88:89], v[2:3], v[72:73]
	v_add_f32_e32 v90, v86, v87
	v_pk_fma_f32 v[82:83], v[54:55], v[46:47], v[78:79] op_sel_hi:[0,1,1]
	v_pk_fma_f32 v[88:89], v[4:5], v[74:75], v[88:89]
	v_add_f32_dpp v90, v90, v90 quad_perm:[1,0,3,2] row_mask:0xf bank_mask:0xf bound_ctrl:1
	v_pk_fma_f32 v[84:85], v[54:55], v[48:49], v[80:81] op_sel_hi:[0,1,1]
	ds_read_b128 v[38:41], v110 offset:5120
	v_add_f32_dpp v90, v90, v90 quad_perm:[2,3,0,1] row_mask:0xf bank_mask:0xf bound_ctrl:1
	ds_read_b128 v[34:37], v110 offset:1024
	v_add_f32_e32 v95, v88, v89
	v_add_f32_dpp v90, v90, v90 row_half_mirror row_mask:0xf bank_mask:0xf bound_ctrl:1
	ds_read_b128 v[72:75], v110 offset:17152
	ds_read_b128 v[46:49], v110 offset:13312
	v_add_f32_dpp v92, v90, v90 row_mirror row_mask:0xf bank_mask:0xf bound_ctrl:1
	ds_read_b32 v54, v111 offset:21504
	v_pk_fma_f32 v[2:3], v[92:93], v[42:43], v[82:83] op_sel_hi:[0,1,1] neg_lo:[1,0,0] neg_hi:[1,0,0]
	v_pk_fma_f32 v[4:5], v[92:93], v[44:45], v[84:85] op_sel_hi:[0,1,1] neg_lo:[1,0,0] neg_hi:[1,0,0]
	ds_read_b128 v[42:45], v110 offset:9216
	s_waitcnt lgkmcnt(6)
	v_pk_mul_f32 v[86:87], v[2:3], v[60:61]
	v_pk_mul_f32 v[78:79], v[2:3], v[56:57]
	v_pk_fma_f32 v[86:87], v[4:5], v[62:63], v[86:87]
	v_pk_mul_f32 v[80:81], v[4:5], v[58:59]
	v_pk_mul_f32 v[88:89], v[2:3], v[50:51]
	v_add_f32_e32 v90, v86, v87
	v_pk_fma_f32 v[82:83], v[76:77], v[68:69], v[78:79] op_sel_hi:[0,1,1]
	v_pk_fma_f32 v[88:89], v[4:5], v[52:53], v[88:89]
	v_add_f32_dpp v90, v90, v90 quad_perm:[1,0,3,2] row_mask:0xf bank_mask:0xf bound_ctrl:1
	v_pk_fma_f32 v[84:85], v[76:77], v[70:71], v[80:81] op_sel_hi:[0,1,1]
	ds_read_b128 v[60:63], v110 offset:5376
	v_add_f32_dpp v90, v90, v90 quad_perm:[2,3,0,1] row_mask:0xf bank_mask:0xf bound_ctrl:1
	ds_read_b128 v[56:59], v110 offset:1280
	v_add_f32_e32 v96, v88, v89
	v_add_f32_dpp v90, v90, v90 row_half_mirror row_mask:0xf bank_mask:0xf bound_ctrl:1
	ds_read_b128 v[50:53], v110 offset:17408
	ds_read_b128 v[68:71], v110 offset:13568
	v_add_f32_dpp v92, v90, v90 row_mirror row_mask:0xf bank_mask:0xf bound_ctrl:1
	ds_read_b32 v76, v111 offset:21760
	v_pk_fma_f32 v[2:3], v[92:93], v[64:65], v[82:83] op_sel_hi:[0,1,1] neg_lo:[1,0,0] neg_hi:[1,0,0]
	v_pk_fma_f32 v[4:5], v[92:93], v[66:67], v[84:85] op_sel_hi:[0,1,1] neg_lo:[1,0,0] neg_hi:[1,0,0]
	ds_read_b128 v[64:67], v110 offset:9472
	s_waitcnt lgkmcnt(6)
	v_pk_mul_f32 v[86:87], v[2:3], v[38:39]
	v_pk_mul_f32 v[78:79], v[2:3], v[34:35]
	v_pk_fma_f32 v[86:87], v[4:5], v[40:41], v[86:87]
	v_pk_mul_f32 v[80:81], v[4:5], v[36:37]
	v_pk_mul_f32 v[88:89], v[2:3], v[72:73]
	v_add_f32_e32 v90, v86, v87
	v_pk_fma_f32 v[82:83], v[54:55], v[46:47], v[78:79] op_sel_hi:[0,1,1]
	v_pk_fma_f32 v[88:89], v[4:5], v[74:75], v[88:89]
	v_add_f32_dpp v90, v90, v90 quad_perm:[1,0,3,2] row_mask:0xf bank_mask:0xf bound_ctrl:1
	v_pk_fma_f32 v[84:85], v[54:55], v[48:49], v[80:81] op_sel_hi:[0,1,1]
	ds_read_b128 v[38:41], v110 offset:5632
	v_add_f32_dpp v90, v90, v90 quad_perm:[2,3,0,1] row_mask:0xf bank_mask:0xf bound_ctrl:1
	ds_read_b128 v[34:37], v110 offset:1536
	v_add_f32_e32 v97, v88, v89
	v_add_f32_dpp v90, v90, v90 row_half_mirror row_mask:0xf bank_mask:0xf bound_ctrl:1
	ds_read_b128 v[72:75], v110 offset:17664
	ds_read_b128 v[46:49], v110 offset:13824
	v_add_f32_dpp v92, v90, v90 row_mirror row_mask:0xf bank_mask:0xf bound_ctrl:1
	ds_read_b32 v54, v111 offset:22016
	v_pk_fma_f32 v[2:3], v[92:93], v[42:43], v[82:83] op_sel_hi:[0,1,1] neg_lo:[1,0,0] neg_hi:[1,0,0]
	v_pk_fma_f32 v[4:5], v[92:93], v[44:45], v[84:85] op_sel_hi:[0,1,1] neg_lo:[1,0,0] neg_hi:[1,0,0]
	ds_read_b128 v[42:45], v110 offset:9728
	s_waitcnt lgkmcnt(6)
	v_pk_mul_f32 v[86:87], v[2:3], v[60:61]
	v_pk_mul_f32 v[78:79], v[2:3], v[56:57]
	v_pk_fma_f32 v[86:87], v[4:5], v[62:63], v[86:87]
	v_pk_mul_f32 v[80:81], v[4:5], v[58:59]
	v_pk_mul_f32 v[88:89], v[2:3], v[50:51]
	v_add_f32_e32 v90, v86, v87
	v_pk_fma_f32 v[82:83], v[76:77], v[68:69], v[78:79] op_sel_hi:[0,1,1]
	v_pk_fma_f32 v[88:89], v[4:5], v[52:53], v[88:89]
	v_add_f32_dpp v90, v90, v90 quad_perm:[1,0,3,2] row_mask:0xf bank_mask:0xf bound_ctrl:1
	v_pk_fma_f32 v[84:85], v[76:77], v[70:71], v[80:81] op_sel_hi:[0,1,1]
	ds_read_b128 v[60:63], v110 offset:5888
	v_add_f32_dpp v90, v90, v90 quad_perm:[2,3,0,1] row_mask:0xf bank_mask:0xf bound_ctrl:1
	ds_read_b128 v[56:59], v110 offset:1792
	v_add_f32_e32 v98, v88, v89
	v_add_f32_dpp v90, v90, v90 row_half_mirror row_mask:0xf bank_mask:0xf bound_ctrl:1
	ds_read_b128 v[50:53], v110 offset:17920
	ds_read_b128 v[68:71], v110 offset:14080
	v_add_f32_dpp v92, v90, v90 row_mirror row_mask:0xf bank_mask:0xf bound_ctrl:1
	ds_read_b32 v76, v111 offset:22272
	v_pk_fma_f32 v[2:3], v[92:93], v[64:65], v[82:83] op_sel_hi:[0,1,1] neg_lo:[1,0,0] neg_hi:[1,0,0]
	v_pk_fma_f32 v[4:5], v[92:93], v[66:67], v[84:85] op_sel_hi:[0,1,1] neg_lo:[1,0,0] neg_hi:[1,0,0]
	ds_read_b128 v[64:67], v110 offset:9984
	s_waitcnt lgkmcnt(6)
	v_pk_mul_f32 v[86:87], v[2:3], v[38:39]
	v_pk_mul_f32 v[78:79], v[2:3], v[34:35]
	v_pk_fma_f32 v[86:87], v[4:5], v[40:41], v[86:87]
	v_pk_mul_f32 v[80:81], v[4:5], v[36:37]
	v_pk_mul_f32 v[88:89], v[2:3], v[72:73]
	v_add_f32_e32 v90, v86, v87
	v_pk_fma_f32 v[82:83], v[54:55], v[46:47], v[78:79] op_sel_hi:[0,1,1]
	v_pk_fma_f32 v[88:89], v[4:5], v[74:75], v[88:89]
	v_add_f32_dpp v90, v90, v90 quad_perm:[1,0,3,2] row_mask:0xf bank_mask:0xf bound_ctrl:1
	v_pk_fma_f32 v[84:85], v[54:55], v[48:49], v[80:81] op_sel_hi:[0,1,1]
	ds_read_b128 v[38:41], v110 offset:6144
	v_add_f32_dpp v90, v90, v90 quad_perm:[2,3,0,1] row_mask:0xf bank_mask:0xf bound_ctrl:1
	ds_read_b128 v[34:37], v110 offset:2048
	v_add_f32_e32 v99, v88, v89
	v_add_f32_dpp v90, v90, v90 row_half_mirror row_mask:0xf bank_mask:0xf bound_ctrl:1
	ds_read_b128 v[72:75], v110 offset:18176
	ds_read_b128 v[46:49], v110 offset:14336
	v_add_f32_dpp v92, v90, v90 row_mirror row_mask:0xf bank_mask:0xf bound_ctrl:1
	ds_read_b32 v54, v111 offset:22528
	v_pk_fma_f32 v[2:3], v[92:93], v[42:43], v[82:83] op_sel_hi:[0,1,1] neg_lo:[1,0,0] neg_hi:[1,0,0]
	v_pk_fma_f32 v[4:5], v[92:93], v[44:45], v[84:85] op_sel_hi:[0,1,1] neg_lo:[1,0,0] neg_hi:[1,0,0]
	ds_read_b128 v[42:45], v110 offset:10240
	s_waitcnt lgkmcnt(6)
	v_pk_mul_f32 v[86:87], v[2:3], v[60:61]
	v_pk_mul_f32 v[78:79], v[2:3], v[56:57]
	v_pk_fma_f32 v[86:87], v[4:5], v[62:63], v[86:87]
	v_pk_mul_f32 v[80:81], v[4:5], v[58:59]
	v_pk_mul_f32 v[88:89], v[2:3], v[50:51]
	v_add_f32_e32 v90, v86, v87
	v_pk_fma_f32 v[82:83], v[76:77], v[68:69], v[78:79] op_sel_hi:[0,1,1]
	v_pk_fma_f32 v[88:89], v[4:5], v[52:53], v[88:89]
	v_add_f32_dpp v90, v90, v90 quad_perm:[1,0,3,2] row_mask:0xf bank_mask:0xf bound_ctrl:1
	v_pk_fma_f32 v[84:85], v[76:77], v[70:71], v[80:81] op_sel_hi:[0,1,1]
	ds_read_b128 v[60:63], v110 offset:6400
	v_add_f32_dpp v90, v90, v90 quad_perm:[2,3,0,1] row_mask:0xf bank_mask:0xf bound_ctrl:1
	ds_read_b128 v[56:59], v110 offset:2304
	v_add_f32_e32 v100, v88, v89
	v_add_f32_dpp v90, v90, v90 row_half_mirror row_mask:0xf bank_mask:0xf bound_ctrl:1
	ds_read_b128 v[50:53], v110 offset:18432
	ds_read_b128 v[68:71], v110 offset:14592
	v_add_f32_dpp v92, v90, v90 row_mirror row_mask:0xf bank_mask:0xf bound_ctrl:1
	ds_read_b32 v76, v111 offset:22784
	v_pk_fma_f32 v[2:3], v[92:93], v[64:65], v[82:83] op_sel_hi:[0,1,1] neg_lo:[1,0,0] neg_hi:[1,0,0]
	v_pk_fma_f32 v[4:5], v[92:93], v[66:67], v[84:85] op_sel_hi:[0,1,1] neg_lo:[1,0,0] neg_hi:[1,0,0]
	ds_read_b128 v[64:67], v110 offset:10496
	s_waitcnt lgkmcnt(6)
	v_pk_mul_f32 v[86:87], v[2:3], v[38:39]
	v_pk_mul_f32 v[78:79], v[2:3], v[34:35]
	v_pk_fma_f32 v[86:87], v[4:5], v[40:41], v[86:87]
	v_pk_mul_f32 v[80:81], v[4:5], v[36:37]
	v_pk_mul_f32 v[88:89], v[2:3], v[72:73]
	v_add_f32_e32 v90, v86, v87
	v_pk_fma_f32 v[82:83], v[54:55], v[46:47], v[78:79] op_sel_hi:[0,1,1]
	v_pk_fma_f32 v[88:89], v[4:5], v[74:75], v[88:89]
	v_add_f32_dpp v90, v90, v90 quad_perm:[1,0,3,2] row_mask:0xf bank_mask:0xf bound_ctrl:1
	v_pk_fma_f32 v[84:85], v[54:55], v[48:49], v[80:81] op_sel_hi:[0,1,1]
	ds_read_b128 v[38:41], v110 offset:6656
	v_add_f32_dpp v90, v90, v90 quad_perm:[2,3,0,1] row_mask:0xf bank_mask:0xf bound_ctrl:1
	ds_read_b128 v[34:37], v110 offset:2560
	v_add_f32_e32 v101, v88, v89
	v_add_f32_dpp v90, v90, v90 row_half_mirror row_mask:0xf bank_mask:0xf bound_ctrl:1
	ds_read_b128 v[72:75], v110 offset:18688
	ds_read_b128 v[46:49], v110 offset:14848
	v_add_f32_dpp v92, v90, v90 row_mirror row_mask:0xf bank_mask:0xf bound_ctrl:1
	ds_read_b32 v54, v111 offset:23040
	v_pk_fma_f32 v[2:3], v[92:93], v[42:43], v[82:83] op_sel_hi:[0,1,1] neg_lo:[1,0,0] neg_hi:[1,0,0]
	v_pk_fma_f32 v[4:5], v[92:93], v[44:45], v[84:85] op_sel_hi:[0,1,1] neg_lo:[1,0,0] neg_hi:[1,0,0]
	ds_read_b128 v[42:45], v110 offset:10752
	s_waitcnt lgkmcnt(6)
	v_pk_mul_f32 v[86:87], v[2:3], v[60:61]
	v_pk_mul_f32 v[78:79], v[2:3], v[56:57]
	v_pk_fma_f32 v[86:87], v[4:5], v[62:63], v[86:87]
	v_pk_mul_f32 v[80:81], v[4:5], v[58:59]
	v_pk_mul_f32 v[88:89], v[2:3], v[50:51]
	v_add_f32_e32 v90, v86, v87
	v_pk_fma_f32 v[82:83], v[76:77], v[68:69], v[78:79] op_sel_hi:[0,1,1]
	v_pk_fma_f32 v[88:89], v[4:5], v[52:53], v[88:89]
	v_add_f32_dpp v90, v90, v90 quad_perm:[1,0,3,2] row_mask:0xf bank_mask:0xf bound_ctrl:1
	v_pk_fma_f32 v[84:85], v[76:77], v[70:71], v[80:81] op_sel_hi:[0,1,1]
	ds_read_b128 v[60:63], v110 offset:6912
	v_add_f32_dpp v90, v90, v90 quad_perm:[2,3,0,1] row_mask:0xf bank_mask:0xf bound_ctrl:1
	ds_read_b128 v[56:59], v110 offset:2816
	v_add_f32_e32 v102, v88, v89
	v_add_f32_dpp v90, v90, v90 row_half_mirror row_mask:0xf bank_mask:0xf bound_ctrl:1
	ds_read_b128 v[50:53], v110 offset:18944
	ds_read_b128 v[68:71], v110 offset:15104
	v_add_f32_dpp v92, v90, v90 row_mirror row_mask:0xf bank_mask:0xf bound_ctrl:1
	ds_read_b32 v76, v111 offset:23296
	v_pk_fma_f32 v[2:3], v[92:93], v[64:65], v[82:83] op_sel_hi:[0,1,1] neg_lo:[1,0,0] neg_hi:[1,0,0]
	v_pk_fma_f32 v[4:5], v[92:93], v[66:67], v[84:85] op_sel_hi:[0,1,1] neg_lo:[1,0,0] neg_hi:[1,0,0]
	ds_read_b128 v[64:67], v110 offset:11008
	s_waitcnt lgkmcnt(6)
	v_pk_mul_f32 v[86:87], v[2:3], v[38:39]
	v_pk_mul_f32 v[78:79], v[2:3], v[34:35]
	v_pk_fma_f32 v[86:87], v[4:5], v[40:41], v[86:87]
	v_pk_mul_f32 v[80:81], v[4:5], v[36:37]
	v_pk_mul_f32 v[88:89], v[2:3], v[72:73]
	v_add_f32_e32 v90, v86, v87
	v_pk_fma_f32 v[82:83], v[54:55], v[46:47], v[78:79] op_sel_hi:[0,1,1]
	v_pk_fma_f32 v[88:89], v[4:5], v[74:75], v[88:89]
	v_add_f32_dpp v90, v90, v90 quad_perm:[1,0,3,2] row_mask:0xf bank_mask:0xf bound_ctrl:1
	v_pk_fma_f32 v[84:85], v[54:55], v[48:49], v[80:81] op_sel_hi:[0,1,1]
	ds_read_b128 v[38:41], v110 offset:7168
	v_add_f32_dpp v90, v90, v90 quad_perm:[2,3,0,1] row_mask:0xf bank_mask:0xf bound_ctrl:1
	ds_read_b128 v[34:37], v110 offset:3072
	v_add_f32_e32 v103, v88, v89
	v_add_f32_dpp v90, v90, v90 row_half_mirror row_mask:0xf bank_mask:0xf bound_ctrl:1
	ds_read_b128 v[72:75], v110 offset:19200
	ds_read_b128 v[46:49], v110 offset:15360
	v_add_f32_dpp v92, v90, v90 row_mirror row_mask:0xf bank_mask:0xf bound_ctrl:1
	ds_read_b32 v54, v111 offset:23552
	v_pk_fma_f32 v[2:3], v[92:93], v[42:43], v[82:83] op_sel_hi:[0,1,1] neg_lo:[1,0,0] neg_hi:[1,0,0]
	v_pk_fma_f32 v[4:5], v[92:93], v[44:45], v[84:85] op_sel_hi:[0,1,1] neg_lo:[1,0,0] neg_hi:[1,0,0]
	ds_read_b128 v[42:45], v110 offset:11264
	s_waitcnt lgkmcnt(6)
	v_pk_mul_f32 v[86:87], v[2:3], v[60:61]
	v_pk_mul_f32 v[78:79], v[2:3], v[56:57]
	v_pk_fma_f32 v[86:87], v[4:5], v[62:63], v[86:87]
	v_pk_mul_f32 v[80:81], v[4:5], v[58:59]
	v_pk_mul_f32 v[88:89], v[2:3], v[50:51]
	v_add_f32_e32 v90, v86, v87
	v_pk_fma_f32 v[82:83], v[76:77], v[68:69], v[78:79] op_sel_hi:[0,1,1]
	v_pk_fma_f32 v[88:89], v[4:5], v[52:53], v[88:89]
	v_add_f32_dpp v90, v90, v90 quad_perm:[1,0,3,2] row_mask:0xf bank_mask:0xf bound_ctrl:1
	v_pk_fma_f32 v[84:85], v[76:77], v[70:71], v[80:81] op_sel_hi:[0,1,1]
	ds_read_b128 v[60:63], v110 offset:7424
	v_add_f32_dpp v90, v90, v90 quad_perm:[2,3,0,1] row_mask:0xf bank_mask:0xf bound_ctrl:1
	ds_read_b128 v[56:59], v110 offset:3328
	v_add_f32_e32 v104, v88, v89
	v_add_f32_dpp v90, v90, v90 row_half_mirror row_mask:0xf bank_mask:0xf bound_ctrl:1
	ds_read_b128 v[50:53], v110 offset:19456
	ds_read_b128 v[68:71], v110 offset:15616
	v_add_f32_dpp v92, v90, v90 row_mirror row_mask:0xf bank_mask:0xf bound_ctrl:1
	ds_read_b32 v76, v111 offset:23808
	v_pk_fma_f32 v[2:3], v[92:93], v[64:65], v[82:83] op_sel_hi:[0,1,1] neg_lo:[1,0,0] neg_hi:[1,0,0]
	v_pk_fma_f32 v[4:5], v[92:93], v[66:67], v[84:85] op_sel_hi:[0,1,1] neg_lo:[1,0,0] neg_hi:[1,0,0]
	ds_read_b128 v[64:67], v110 offset:11520
	s_waitcnt lgkmcnt(6)
	v_pk_mul_f32 v[86:87], v[2:3], v[38:39]
	v_pk_mul_f32 v[78:79], v[2:3], v[34:35]
	v_pk_fma_f32 v[86:87], v[4:5], v[40:41], v[86:87]
	v_pk_mul_f32 v[80:81], v[4:5], v[36:37]
	v_pk_mul_f32 v[88:89], v[2:3], v[72:73]
	v_add_f32_e32 v90, v86, v87
	v_pk_fma_f32 v[82:83], v[54:55], v[46:47], v[78:79] op_sel_hi:[0,1,1]
	v_pk_fma_f32 v[88:89], v[4:5], v[74:75], v[88:89]
	v_add_f32_dpp v90, v90, v90 quad_perm:[1,0,3,2] row_mask:0xf bank_mask:0xf bound_ctrl:1
	v_pk_fma_f32 v[84:85], v[54:55], v[48:49], v[80:81] op_sel_hi:[0,1,1]
	ds_read_b128 v[38:41], v110 offset:7680
	v_add_f32_dpp v90, v90, v90 quad_perm:[2,3,0,1] row_mask:0xf bank_mask:0xf bound_ctrl:1
	ds_read_b128 v[34:37], v110 offset:3584
	v_add_f32_e32 v105, v88, v89
	v_add_f32_dpp v90, v90, v90 row_half_mirror row_mask:0xf bank_mask:0xf bound_ctrl:1
	ds_read_b128 v[72:75], v110 offset:19712
	ds_read_b128 v[46:49], v110 offset:15872
	v_add_f32_dpp v92, v90, v90 row_mirror row_mask:0xf bank_mask:0xf bound_ctrl:1
	ds_read_b32 v54, v111 offset:24064
	v_pk_fma_f32 v[2:3], v[92:93], v[42:43], v[82:83] op_sel_hi:[0,1,1] neg_lo:[1,0,0] neg_hi:[1,0,0]
	v_pk_fma_f32 v[4:5], v[92:93], v[44:45], v[84:85] op_sel_hi:[0,1,1] neg_lo:[1,0,0] neg_hi:[1,0,0]
	ds_read_b128 v[42:45], v110 offset:11776
	s_waitcnt lgkmcnt(6)
	v_pk_mul_f32 v[86:87], v[2:3], v[60:61]
	v_pk_mul_f32 v[78:79], v[2:3], v[56:57]
	v_pk_fma_f32 v[86:87], v[4:5], v[62:63], v[86:87]
	v_pk_mul_f32 v[80:81], v[4:5], v[58:59]
	v_pk_mul_f32 v[88:89], v[2:3], v[50:51]
	v_add_f32_e32 v90, v86, v87
	v_pk_fma_f32 v[82:83], v[76:77], v[68:69], v[78:79] op_sel_hi:[0,1,1]
	v_pk_fma_f32 v[88:89], v[4:5], v[52:53], v[88:89]
	v_add_f32_dpp v90, v90, v90 quad_perm:[1,0,3,2] row_mask:0xf bank_mask:0xf bound_ctrl:1
	v_pk_fma_f32 v[84:85], v[76:77], v[70:71], v[80:81] op_sel_hi:[0,1,1]
	ds_read_b128 v[60:63], v110 offset:7936
	v_add_f32_dpp v90, v90, v90 quad_perm:[2,3,0,1] row_mask:0xf bank_mask:0xf bound_ctrl:1
	ds_read_b128 v[56:59], v110 offset:3840
	v_add_f32_e32 v106, v88, v89
	v_add_f32_dpp v90, v90, v90 row_half_mirror row_mask:0xf bank_mask:0xf bound_ctrl:1
	ds_read_b128 v[50:53], v110 offset:19968
	ds_read_b128 v[68:71], v110 offset:16128
	v_add_f32_dpp v92, v90, v90 row_mirror row_mask:0xf bank_mask:0xf bound_ctrl:1
	ds_read_b32 v76, v111 offset:24320
	s_cmpk_eq_i32 s33, 0x10f
	s_cbranch_scc1 .Lscan_tail_last
	v_pk_fma_f32 v[2:3], v[92:93], v[64:65], v[82:83] op_sel_hi:[0,1,1] neg_lo:[1,0,0] neg_hi:[1,0,0]
	v_pk_fma_f32 v[4:5], v[92:93], v[66:67], v[84:85] op_sel_hi:[0,1,1] neg_lo:[1,0,0] neg_hi:[1,0,0]
	ds_read_b128 v[64:67], v110 offset:12032
	s_waitcnt lgkmcnt(6)
	v_pk_mul_f32 v[86:87], v[2:3], v[38:39]
	v_pk_mul_f32 v[78:79], v[2:3], v[34:35]
	v_pk_fma_f32 v[86:87], v[4:5], v[40:41], v[86:87]
	v_pk_mul_f32 v[80:81], v[4:5], v[36:37]
	v_pk_mul_f32 v[88:89], v[2:3], v[72:73]
	v_add_f32_e32 v90, v86, v87
	v_pk_fma_f32 v[82:83], v[54:55], v[46:47], v[78:79] op_sel_hi:[0,1,1]
	v_pk_fma_f32 v[88:89], v[4:5], v[74:75], v[88:89]
	v_add_f32_dpp v90, v90, v90 quad_perm:[1,0,3,2] row_mask:0xf bank_mask:0xf bound_ctrl:1
	v_pk_fma_f32 v[84:85], v[54:55], v[48:49], v[80:81] op_sel_hi:[0,1,1]
	s_waitcnt vmcnt(18)
	v_add_f32_dpp v90, v90, v90 quad_perm:[2,3,0,1] row_mask:0xf bank_mask:0xf bound_ctrl:1
	v_pk_add_f32 v[122:123], v[198:199], -1.0 op_sel_hi:[1,0]
	v_add_f32_e32 v107, v88, v89
	v_add_f32_dpp v90, v90, v90 row_half_mirror row_mask:0xf bank_mask:0xf bound_ctrl:1
	ds_read_b128 v[72:75], v110 offset:20224
	v_pk_add_f32 v[124:125], v[200:201], -1.0 op_sel_hi:[1,0]
	v_add_f32_dpp v92, v90, v90 row_mirror row_mask:0xf bank_mask:0xf bound_ctrl:1
	v_pk_mul_f32 v[118:119], v[202:203], v[198:199]
	v_pk_fma_f32 v[2:3], v[92:93], v[42:43], v[82:83] op_sel_hi:[0,1,1] neg_lo:[1,0,0] neg_hi:[1,0,0]
	v_pk_fma_f32 v[4:5], v[92:93], v[44:45], v[84:85] op_sel_hi:[0,1,1] neg_lo:[1,0,0] neg_hi:[1,0,0]
	v_pk_fma_f32 v[122:123], v[6:7], v[122:123], 1.0 op_sel_hi:[1,1,0]
	s_waitcnt lgkmcnt(1)
	v_pk_mul_f32 v[86:87], v[2:3], v[60:61]
	v_pk_mul_f32 v[78:79], v[2:3], v[56:57]
	v_pk_fma_f32 v[86:87], v[4:5], v[62:63], v[86:87]
	v_pk_mul_f32 v[80:81], v[4:5], v[58:59]
	v_pk_mul_f32 v[88:89], v[2:3], v[50:51]
	v_add_f32_e32 v90, v86, v87
	v_pk_fma_f32 v[82:83], v[76:77], v[68:69], v[78:79] op_sel_hi:[0,1,1]
	v_pk_fma_f32 v[88:89], v[4:5], v[52:53], v[88:89]
	v_add_f32_dpp v90, v90, v90 quad_perm:[1,0,3,2] row_mask:0xf bank_mask:0xf bound_ctrl:1
	v_pk_fma_f32 v[84:85], v[76:77], v[70:71], v[80:81] op_sel_hi:[0,1,1]
	v_pk_fma_f32 v[124:125], v[8:9], v[124:125], 1.0 op_sel_hi:[1,1,0]
	v_add_f32_dpp v90, v90, v90 quad_perm:[2,3,0,1] row_mask:0xf bank_mask:0xf bound_ctrl:1
	v_pk_mul_f32 v[120:121], v[204:205], v[200:201]
	v_add_f32_e32 v108, v88, v89
	v_add_f32_dpp v90, v90, v90 row_half_mirror row_mask:0xf bank_mask:0xf bound_ctrl:1
	v_pk_mul_f32 v[122:123], v[186:187], v[122:123]
	v_pk_mul_f32 v[124:125], v[188:189], v[124:125]
	v_add_f32_dpp v92, v90, v90 row_mirror row_mask:0xf bank_mask:0xf bound_ctrl:1
	ds_write_b128 v112, v[194:197] offset:0
	ds_write_b128 v112, v[202:205] offset:4096
	v_pk_fma_f32 v[2:3], v[92:93], v[64:65], v[82:83] op_sel_hi:[0,1,1] neg_lo:[1,0,0] neg_hi:[1,0,0]
	v_pk_fma_f32 v[4:5], v[92:93], v[66:67], v[84:85] op_sel_hi:[0,1,1] neg_lo:[1,0,0] neg_hi:[1,0,0]
	ds_write_b128 v112, v[182:185] offset:16384
	s_waitcnt lgkmcnt(3)
	v_pk_mul_f32 v[88:89], v[2:3], v[72:73]
	ds_write_b128 v112, v[190:193] offset:20480
	v_pk_fma_f32 v[88:89], v[4:5], v[74:75], v[88:89]
	ds_write_b128 v112, v[118:121] offset:8192
	v_add_f32_e32 v109, v88, v89
	ds_write_b128 v112, v[122:125] offset:12288
	s_waitcnt lgkmcnt(0)
	v_xor_b32_e32 v110, 0x6000, v110
	v_xor_b32_e32 v111, 0x6000, v111
	v_xor_b32_e32 v112, 0x6000, v112
	s_add_i32 s33, s33, 1
	s_barrier
	ds_read_b128 v[38:41], v110 offset:4096
	ds_read_b128 v[34:37], v110 offset:0
	ds_read_b128 v[46:49], v110 offset:12288
	ds_read_b32 v54, v111 offset:20480
	ds_read_b128 v[42:45], v110 offset:8192
	ds_read_b128 v[50:53], v110 offset:16384
	ds_read_b128 v[60:63], v110 offset:4352
	ds_read_b128 v[56:59], v110 offset:256
	ds_read_b128 v[68:71], v110 offset:12544
	ds_read_b32 v76, v111 offset:20736
	ds_read_b128 v[64:67], v110 offset:8448
	ds_read_b128 v[72:75], v110 offset:16640
	s_cmpk_ge_i32 s33, 0x10c
	s_cbranch_scc1 .Lscan_skipload_c2
	v_mul_u32_u24_e32 v0, 0xf00, v113
	v_lshl_add_u32 v125, v113, 10, v115
	v_add_u32_e32 v0, v0, v115
	v_add_u32_e32 v113, s34, v113
	global_load_dwordx4 v[194:197], v125, s[46:47]
	global_load_dwordx4 v[198:201], v125, s[48:49]
	global_load_dwordx4 v[202:205], v125, s[22:23]
	global_load_dwordx4 v[186:189], v0, s[12:13] offset:1024
	global_load_dwordx4 v[182:185], v0, s[12:13]
	global_load_dwordx4 v[190:193], v0, s[12:13] offset:2048
	s_cmp_eq_u32 s33, 11
	s_cbranch_scc0 .Lscan_nogload_c2
	v_mov_b32_e32 v113, v117
	s_branch .Lscan_nogload_c2

.Lscan_nored_c2:
	s_waitcnt lgkmcnt(1)
	v_pk_mul_f32 v[86:87], v[2:3], v[38:39]
	v_pk_mul_f32 v[78:79], v[2:3], v[34:35]
	v_pk_fma_f32 v[86:87], v[4:5], v[40:41], v[86:87]
	v_pk_mul_f32 v[80:81], v[4:5], v[36:37]
	ds_read_b128 v[38:41], v110 offset:4608
	v_add_f32_e32 v90, v86, v87
	v_pk_fma_f32 v[82:83], v[54:55], v[46:47], v[78:79] op_sel_hi:[0,1,1]
	ds_read_b128 v[34:37], v110 offset:512
	v_add_f32_dpp v90, v90, v90 quad_perm:[1,0,3,2] row_mask:0xf bank_mask:0xf bound_ctrl:1
	v_pk_fma_f32 v[84:85], v[54:55], v[48:49], v[80:81] op_sel_hi:[0,1,1]
	ds_read_b128 v[46:49], v110 offset:12800
	v_add_f32_dpp v90, v90, v90 quad_perm:[2,3,0,1] row_mask:0xf bank_mask:0xf bound_ctrl:1
	ds_read_b32 v54, v111 offset:20992
	s_nop 0
	v_add_f32_dpp v90, v90, v90 row_half_mirror row_mask:0xf bank_mask:0xf bound_ctrl:1
	s_nop 0
	s_nop 0
	v_add_f32_dpp v92, v90, v90 row_mirror row_mask:0xf bank_mask:0xf bound_ctrl:1
	v_pk_fma_f32 v[2:3], v[92:93], v[42:43], v[82:83] op_sel_hi:[0,1,1] neg_lo:[1,0,0] neg_hi:[1,0,0]
	v_pk_fma_f32 v[4:5], v[92:93], v[44:45], v[84:85] op_sel_hi:[0,1,1] neg_lo:[1,0,0] neg_hi:[1,0,0]
	ds_read_b128 v[42:45], v110 offset:8704
	v_pk_mul_f32 v[86:87], v[2:3], v[60:61]
	v_pk_mul_f32 v[78:79], v[2:3], v[56:57]
	v_pk_fma_f32 v[86:87], v[4:5], v[62:63], v[86:87]
	v_pk_mul_f32 v[80:81], v[4:5], v[58:59]
	v_pk_mul_f32 v[88:89], v[2:3], v[50:51]
	v_add_f32_e32 v90, v86, v87
	v_pk_fma_f32 v[82:83], v[76:77], v[68:69], v[78:79] op_sel_hi:[0,1,1]
	v_pk_fma_f32 v[88:89], v[4:5], v[52:53], v[88:89]
	v_add_f32_dpp v90, v90, v90 quad_perm:[1,0,3,2] row_mask:0xf bank_mask:0xf bound_ctrl:1
	v_pk_fma_f32 v[84:85], v[76:77], v[70:71], v[80:81] op_sel_hi:[0,1,1]
	ds_read_b128 v[60:63], v110 offset:4864
	v_add_f32_dpp v90, v90, v90 quad_perm:[2,3,0,1] row_mask:0xf bank_mask:0xf bound_ctrl:1
	ds_read_b128 v[56:59], v110 offset:768
	v_add_f32_e32 v94, v88, v89
	v_add_f32_dpp v90, v90, v90 row_half_mirror row_mask:0xf bank_mask:0xf bound_ctrl:1
	ds_read_b128 v[50:53], v110 offset:16896
	ds_read_b128 v[68:71], v110 offset:13056
	v_add_f32_dpp v92, v90, v90 row_mirror row_mask:0xf bank_mask:0xf bound_ctrl:1
	ds_read_b32 v76, v111 offset:21248
	v_pk_fma_f32 v[2:3], v[92:93], v[64:65], v[82:83] op_sel_hi:[0,1,1] neg_lo:[1,0,0] neg_hi:[1,0,0]
	v_pk_fma_f32 v[4:5], v[92:93], v[66:67], v[84:85] op_sel_hi:[0,1,1] neg_lo:[1,0,0] neg_hi:[1,0,0]
	ds_read_b128 v[64:67], v110 offset:8960
	s_waitcnt lgkmcnt(6)
	v_pk_mul_f32 v[86:87], v[2:3], v[38:39]
	v_pk_mul_f32 v[78:79], v[2:3], v[34:35]
	v_pk_fma_f32 v[86:87], v[4:5], v[40:41], v[86:87]
	v_pk_mul_f32 v[80:81], v[4:5], v[36:37]
	v_pk_mul_f32 v[88:89], v[2:3], v[72:73]
	v_add_f32_e32 v90, v86, v87
	v_pk_fma_f32 v[82:83], v[54:55], v[46:47], v[78:79] op_sel_hi:[0,1,1]
	v_pk_fma_f32 v[88:89], v[4:5], v[74:75], v[88:89]
	v_add_f32_dpp v90, v90, v90 quad_perm:[1,0,3,2] row_mask:0xf bank_mask:0xf bound_ctrl:1
	v_pk_fma_f32 v[84:85], v[54:55], v[48:49], v[80:81] op_sel_hi:[0,1,1]
	ds_read_b128 v[38:41], v110 offset:5120
	v_add_f32_dpp v90, v90, v90 quad_perm:[2,3,0,1] row_mask:0xf bank_mask:0xf bound_ctrl:1
	ds_read_b128 v[34:37], v110 offset:1024
	v_add_f32_e32 v95, v88, v89
	v_add_f32_dpp v90, v90, v90 row_half_mirror row_mask:0xf bank_mask:0xf bound_ctrl:1
	ds_read_b128 v[72:75], v110 offset:17152
	ds_read_b128 v[46:49], v110 offset:13312
	v_add_f32_dpp v92, v90, v90 row_mirror row_mask:0xf bank_mask:0xf bound_ctrl:1
	ds_read_b32 v54, v111 offset:21504
	v_pk_fma_f32 v[2:3], v[92:93], v[42:43], v[82:83] op_sel_hi:[0,1,1] neg_lo:[1,0,0] neg_hi:[1,0,0]
	v_pk_fma_f32 v[4:5], v[92:93], v[44:45], v[84:85] op_sel_hi:[0,1,1] neg_lo:[1,0,0] neg_hi:[1,0,0]
	ds_read_b128 v[42:45], v110 offset:9216
	s_waitcnt lgkmcnt(6)
	v_pk_mul_f32 v[86:87], v[2:3], v[60:61]
	v_pk_mul_f32 v[78:79], v[2:3], v[56:57]
	v_pk_fma_f32 v[86:87], v[4:5], v[62:63], v[86:87]
	v_pk_mul_f32 v[80:81], v[4:5], v[58:59]
	v_pk_mul_f32 v[88:89], v[2:3], v[50:51]
	v_add_f32_e32 v90, v86, v87
	v_pk_fma_f32 v[82:83], v[76:77], v[68:69], v[78:79] op_sel_hi:[0,1,1]
	v_pk_fma_f32 v[88:89], v[4:5], v[52:53], v[88:89]
	v_add_f32_dpp v90, v90, v90 quad_perm:[1,0,3,2] row_mask:0xf bank_mask:0xf bound_ctrl:1
	v_pk_fma_f32 v[84:85], v[76:77], v[70:71], v[80:81] op_sel_hi:[0,1,1]
	ds_read_b128 v[60:63], v110 offset:5376
	v_add_f32_dpp v90, v90, v90 quad_perm:[2,3,0,1] row_mask:0xf bank_mask:0xf bound_ctrl:1
	ds_read_b128 v[56:59], v110 offset:1280
	v_add_f32_e32 v96, v88, v89
	v_add_f32_dpp v90, v90, v90 row_half_mirror row_mask:0xf bank_mask:0xf bound_ctrl:1
	ds_read_b128 v[50:53], v110 offset:17408
	ds_read_b128 v[68:71], v110 offset:13568
	v_add_f32_dpp v92, v90, v90 row_mirror row_mask:0xf bank_mask:0xf bound_ctrl:1
	ds_read_b32 v76, v111 offset:21760
	v_pk_fma_f32 v[2:3], v[92:93], v[64:65], v[82:83] op_sel_hi:[0,1,1] neg_lo:[1,0,0] neg_hi:[1,0,0]
	v_pk_fma_f32 v[4:5], v[92:93], v[66:67], v[84:85] op_sel_hi:[0,1,1] neg_lo:[1,0,0] neg_hi:[1,0,0]
	ds_read_b128 v[64:67], v110 offset:9472
	s_waitcnt lgkmcnt(6)
	v_pk_mul_f32 v[86:87], v[2:3], v[38:39]
	v_pk_mul_f32 v[78:79], v[2:3], v[34:35]
	v_pk_fma_f32 v[86:87], v[4:5], v[40:41], v[86:87]
	v_pk_mul_f32 v[80:81], v[4:5], v[36:37]
	v_pk_mul_f32 v[88:89], v[2:3], v[72:73]
	v_add_f32_e32 v90, v86, v87
	v_pk_fma_f32 v[82:83], v[54:55], v[46:47], v[78:79] op_sel_hi:[0,1,1]
	v_pk_fma_f32 v[88:89], v[4:5], v[74:75], v[88:89]
	v_add_f32_dpp v90, v90, v90 quad_perm:[1,0,3,2] row_mask:0xf bank_mask:0xf bound_ctrl:1
	v_pk_fma_f32 v[84:85], v[54:55], v[48:49], v[80:81] op_sel_hi:[0,1,1]
	ds_read_b128 v[38:41], v110 offset:5632
	v_add_f32_dpp v90, v90, v90 quad_perm:[2,3,0,1] row_mask:0xf bank_mask:0xf bound_ctrl:1
	ds_read_b128 v[34:37], v110 offset:1536
	v_add_f32_e32 v97, v88, v89
	v_add_f32_dpp v90, v90, v90 row_half_mirror row_mask:0xf bank_mask:0xf bound_ctrl:1
	ds_read_b128 v[72:75], v110 offset:17664
	ds_read_b128 v[46:49], v110 offset:13824
	v_add_f32_dpp v92, v90, v90 row_mirror row_mask:0xf bank_mask:0xf bound_ctrl:1
	ds_read_b32 v54, v111 offset:22016
	v_pk_fma_f32 v[2:3], v[92:93], v[42:43], v[82:83] op_sel_hi:[0,1,1] neg_lo:[1,0,0] neg_hi:[1,0,0]
	v_pk_fma_f32 v[4:5], v[92:93], v[44:45], v[84:85] op_sel_hi:[0,1,1] neg_lo:[1,0,0] neg_hi:[1,0,0]
	ds_read_b128 v[42:45], v110 offset:9728
	s_waitcnt lgkmcnt(6)
	v_pk_mul_f32 v[86:87], v[2:3], v[60:61]
	v_pk_mul_f32 v[78:79], v[2:3], v[56:57]
	v_pk_fma_f32 v[86:87], v[4:5], v[62:63], v[86:87]
	v_pk_mul_f32 v[80:81], v[4:5], v[58:59]
	v_pk_mul_f32 v[88:89], v[2:3], v[50:51]
	v_add_f32_e32 v90, v86, v87
	v_pk_fma_f32 v[82:83], v[76:77], v[68:69], v[78:79] op_sel_hi:[0,1,1]
	v_pk_fma_f32 v[88:89], v[4:5], v[52:53], v[88:89]
	v_add_f32_dpp v90, v90, v90 quad_perm:[1,0,3,2] row_mask:0xf bank_mask:0xf bound_ctrl:1
	v_pk_fma_f32 v[84:85], v[76:77], v[70:71], v[80:81] op_sel_hi:[0,1,1]
	ds_read_b128 v[60:63], v110 offset:5888
	v_add_f32_dpp v90, v90, v90 quad_perm:[2,3,0,1] row_mask:0xf bank_mask:0xf bound_ctrl:1
	ds_read_b128 v[56:59], v110 offset:1792
	v_add_f32_e32 v98, v88, v89
	v_add_f32_dpp v90, v90, v90 row_half_mirror row_mask:0xf bank_mask:0xf bound_ctrl:1
	ds_read_b128 v[50:53], v110 offset:17920
	ds_read_b128 v[68:71], v110 offset:14080
	v_add_f32_dpp v92, v90, v90 row_mirror row_mask:0xf bank_mask:0xf bound_ctrl:1
	ds_read_b32 v76, v111 offset:22272
	v_pk_fma_f32 v[2:3], v[92:93], v[64:65], v[82:83] op_sel_hi:[0,1,1] neg_lo:[1,0,0] neg_hi:[1,0,0]
	v_pk_fma_f32 v[4:5], v[92:93], v[66:67], v[84:85] op_sel_hi:[0,1,1] neg_lo:[1,0,0] neg_hi:[1,0,0]
	ds_read_b128 v[64:67], v110 offset:9984
	s_waitcnt lgkmcnt(6)
	v_pk_mul_f32 v[86:87], v[2:3], v[38:39]
	v_pk_mul_f32 v[78:79], v[2:3], v[34:35]
	v_pk_fma_f32 v[86:87], v[4:5], v[40:41], v[86:87]
	v_pk_mul_f32 v[80:81], v[4:5], v[36:37]
	v_pk_mul_f32 v[88:89], v[2:3], v[72:73]
	v_add_f32_e32 v90, v86, v87
	v_pk_fma_f32 v[82:83], v[54:55], v[46:47], v[78:79] op_sel_hi:[0,1,1]
	v_pk_fma_f32 v[88:89], v[4:5], v[74:75], v[88:89]
	v_add_f32_dpp v90, v90, v90 quad_perm:[1,0,3,2] row_mask:0xf bank_mask:0xf bound_ctrl:1
	v_pk_fma_f32 v[84:85], v[54:55], v[48:49], v[80:81] op_sel_hi:[0,1,1]
	ds_read_b128 v[38:41], v110 offset:6144
	v_add_f32_dpp v90, v90, v90 quad_perm:[2,3,0,1] row_mask:0xf bank_mask:0xf bound_ctrl:1
	ds_read_b128 v[34:37], v110 offset:2048
	v_add_f32_e32 v99, v88, v89
	v_add_f32_dpp v90, v90, v90 row_half_mirror row_mask:0xf bank_mask:0xf bound_ctrl:1
	ds_read_b128 v[72:75], v110 offset:18176
	ds_read_b128 v[46:49], v110 offset:14336
	v_add_f32_dpp v92, v90, v90 row_mirror row_mask:0xf bank_mask:0xf bound_ctrl:1
	ds_read_b32 v54, v111 offset:22528
	v_pk_fma_f32 v[2:3], v[92:93], v[42:43], v[82:83] op_sel_hi:[0,1,1] neg_lo:[1,0,0] neg_hi:[1,0,0]
	v_pk_fma_f32 v[4:5], v[92:93], v[44:45], v[84:85] op_sel_hi:[0,1,1] neg_lo:[1,0,0] neg_hi:[1,0,0]
	ds_read_b128 v[42:45], v110 offset:10240
	s_waitcnt lgkmcnt(6)
	v_pk_mul_f32 v[86:87], v[2:3], v[60:61]
	v_pk_mul_f32 v[78:79], v[2:3], v[56:57]
	v_pk_fma_f32 v[86:87], v[4:5], v[62:63], v[86:87]
	v_pk_mul_f32 v[80:81], v[4:5], v[58:59]
	v_pk_mul_f32 v[88:89], v[2:3], v[50:51]
	v_add_f32_e32 v90, v86, v87
	v_pk_fma_f32 v[82:83], v[76:77], v[68:69], v[78:79] op_sel_hi:[0,1,1]
	v_pk_fma_f32 v[88:89], v[4:5], v[52:53], v[88:89]
	v_add_f32_dpp v90, v90, v90 quad_perm:[1,0,3,2] row_mask:0xf bank_mask:0xf bound_ctrl:1
	v_pk_fma_f32 v[84:85], v[76:77], v[70:71], v[80:81] op_sel_hi:[0,1,1]
	ds_read_b128 v[60:63], v110 offset:6400
	v_add_f32_dpp v90, v90, v90 quad_perm:[2,3,0,1] row_mask:0xf bank_mask:0xf bound_ctrl:1
	ds_read_b128 v[56:59], v110 offset:2304
	v_add_f32_e32 v100, v88, v89
	v_add_f32_dpp v90, v90, v90 row_half_mirror row_mask:0xf bank_mask:0xf bound_ctrl:1
	ds_read_b128 v[50:53], v110 offset:18432
	ds_read_b128 v[68:71], v110 offset:14592
	v_add_f32_dpp v92, v90, v90 row_mirror row_mask:0xf bank_mask:0xf bound_ctrl:1
	ds_read_b32 v76, v111 offset:22784
	v_pk_fma_f32 v[2:3], v[92:93], v[64:65], v[82:83] op_sel_hi:[0,1,1] neg_lo:[1,0,0] neg_hi:[1,0,0]
	v_pk_fma_f32 v[4:5], v[92:93], v[66:67], v[84:85] op_sel_hi:[0,1,1] neg_lo:[1,0,0] neg_hi:[1,0,0]
	ds_read_b128 v[64:67], v110 offset:10496
	s_waitcnt lgkmcnt(6)
	v_pk_mul_f32 v[86:87], v[2:3], v[38:39]
	v_pk_mul_f32 v[78:79], v[2:3], v[34:35]
	v_pk_fma_f32 v[86:87], v[4:5], v[40:41], v[86:87]
	v_pk_mul_f32 v[80:81], v[4:5], v[36:37]
	v_pk_mul_f32 v[88:89], v[2:3], v[72:73]
	v_add_f32_e32 v90, v86, v87
	v_pk_fma_f32 v[82:83], v[54:55], v[46:47], v[78:79] op_sel_hi:[0,1,1]
	v_pk_fma_f32 v[88:89], v[4:5], v[74:75], v[88:89]
	v_add_f32_dpp v90, v90, v90 quad_perm:[1,0,3,2] row_mask:0xf bank_mask:0xf bound_ctrl:1
	v_pk_fma_f32 v[84:85], v[54:55], v[48:49], v[80:81] op_sel_hi:[0,1,1]
	ds_read_b128 v[38:41], v110 offset:6656
	v_add_f32_dpp v90, v90, v90 quad_perm:[2,3,0,1] row_mask:0xf bank_mask:0xf bound_ctrl:1
	ds_read_b128 v[34:37], v110 offset:2560
	v_add_f32_e32 v101, v88, v89
	v_add_f32_dpp v90, v90, v90 row_half_mirror row_mask:0xf bank_mask:0xf bound_ctrl:1
	ds_read_b128 v[72:75], v110 offset:18688
	ds_read_b128 v[46:49], v110 offset:14848
	v_add_f32_dpp v92, v90, v90 row_mirror row_mask:0xf bank_mask:0xf bound_ctrl:1
	ds_read_b32 v54, v111 offset:23040
	v_pk_fma_f32 v[2:3], v[92:93], v[42:43], v[82:83] op_sel_hi:[0,1,1] neg_lo:[1,0,0] neg_hi:[1,0,0]
	v_pk_fma_f32 v[4:5], v[92:93], v[44:45], v[84:85] op_sel_hi:[0,1,1] neg_lo:[1,0,0] neg_hi:[1,0,0]
	ds_read_b128 v[42:45], v110 offset:10752
	s_waitcnt lgkmcnt(6)
	v_pk_mul_f32 v[86:87], v[2:3], v[60:61]
	v_pk_mul_f32 v[78:79], v[2:3], v[56:57]
	v_pk_fma_f32 v[86:87], v[4:5], v[62:63], v[86:87]
	v_pk_mul_f32 v[80:81], v[4:5], v[58:59]
	v_pk_mul_f32 v[88:89], v[2:3], v[50:51]
	v_add_f32_e32 v90, v86, v87
	v_pk_fma_f32 v[82:83], v[76:77], v[68:69], v[78:79] op_sel_hi:[0,1,1]
	v_pk_fma_f32 v[88:89], v[4:5], v[52:53], v[88:89]
	v_add_f32_dpp v90, v90, v90 quad_perm:[1,0,3,2] row_mask:0xf bank_mask:0xf bound_ctrl:1
	v_pk_fma_f32 v[84:85], v[76:77], v[70:71], v[80:81] op_sel_hi:[0,1,1]
	ds_read_b128 v[60:63], v110 offset:6912
	v_add_f32_dpp v90, v90, v90 quad_perm:[2,3,0,1] row_mask:0xf bank_mask:0xf bound_ctrl:1
	ds_read_b128 v[56:59], v110 offset:2816
	v_add_f32_e32 v102, v88, v89
	v_add_f32_dpp v90, v90, v90 row_half_mirror row_mask:0xf bank_mask:0xf bound_ctrl:1
	ds_read_b128 v[50:53], v110 offset:18944
	ds_read_b128 v[68:71], v110 offset:15104
	v_add_f32_dpp v92, v90, v90 row_mirror row_mask:0xf bank_mask:0xf bound_ctrl:1
	ds_read_b32 v76, v111 offset:23296
	v_pk_fma_f32 v[2:3], v[92:93], v[64:65], v[82:83] op_sel_hi:[0,1,1] neg_lo:[1,0,0] neg_hi:[1,0,0]
	v_pk_fma_f32 v[4:5], v[92:93], v[66:67], v[84:85] op_sel_hi:[0,1,1] neg_lo:[1,0,0] neg_hi:[1,0,0]
	ds_read_b128 v[64:67], v110 offset:11008
	s_waitcnt lgkmcnt(6)
	v_pk_mul_f32 v[86:87], v[2:3], v[38:39]
	v_pk_mul_f32 v[78:79], v[2:3], v[34:35]
	v_pk_fma_f32 v[86:87], v[4:5], v[40:41], v[86:87]
	v_pk_mul_f32 v[80:81], v[4:5], v[36:37]
	v_pk_mul_f32 v[88:89], v[2:3], v[72:73]
	v_add_f32_e32 v90, v86, v87
	v_pk_fma_f32 v[82:83], v[54:55], v[46:47], v[78:79] op_sel_hi:[0,1,1]
	v_pk_fma_f32 v[88:89], v[4:5], v[74:75], v[88:89]
	v_add_f32_dpp v90, v90, v90 quad_perm:[1,0,3,2] row_mask:0xf bank_mask:0xf bound_ctrl:1
	v_pk_fma_f32 v[84:85], v[54:55], v[48:49], v[80:81] op_sel_hi:[0,1,1]
	ds_read_b128 v[38:41], v110 offset:7168
	v_add_f32_dpp v90, v90, v90 quad_perm:[2,3,0,1] row_mask:0xf bank_mask:0xf bound_ctrl:1
	ds_read_b128 v[34:37], v110 offset:3072
	v_add_f32_e32 v103, v88, v89
	v_add_f32_dpp v90, v90, v90 row_half_mirror row_mask:0xf bank_mask:0xf bound_ctrl:1
	ds_read_b128 v[72:75], v110 offset:19200
	ds_read_b128 v[46:49], v110 offset:15360
	v_add_f32_dpp v92, v90, v90 row_mirror row_mask:0xf bank_mask:0xf bound_ctrl:1
	ds_read_b32 v54, v111 offset:23552
	v_pk_fma_f32 v[2:3], v[92:93], v[42:43], v[82:83] op_sel_hi:[0,1,1] neg_lo:[1,0,0] neg_hi:[1,0,0]
	v_pk_fma_f32 v[4:5], v[92:93], v[44:45], v[84:85] op_sel_hi:[0,1,1] neg_lo:[1,0,0] neg_hi:[1,0,0]
	ds_read_b128 v[42:45], v110 offset:11264
	s_waitcnt lgkmcnt(6)
	v_pk_mul_f32 v[86:87], v[2:3], v[60:61]
	v_pk_mul_f32 v[78:79], v[2:3], v[56:57]
	v_pk_fma_f32 v[86:87], v[4:5], v[62:63], v[86:87]
	v_pk_mul_f32 v[80:81], v[4:5], v[58:59]
	v_pk_mul_f32 v[88:89], v[2:3], v[50:51]
	v_add_f32_e32 v90, v86, v87
	v_pk_fma_f32 v[82:83], v[76:77], v[68:69], v[78:79] op_sel_hi:[0,1,1]
	v_pk_fma_f32 v[88:89], v[4:5], v[52:53], v[88:89]
	v_add_f32_dpp v90, v90, v90 quad_perm:[1,0,3,2] row_mask:0xf bank_mask:0xf bound_ctrl:1
	v_pk_fma_f32 v[84:85], v[76:77], v[70:71], v[80:81] op_sel_hi:[0,1,1]
	ds_read_b128 v[60:63], v110 offset:7424
	v_add_f32_dpp v90, v90, v90 quad_perm:[2,3,0,1] row_mask:0xf bank_mask:0xf bound_ctrl:1
	ds_read_b128 v[56:59], v110 offset:3328
	v_add_f32_e32 v104, v88, v89
	v_add_f32_dpp v90, v90, v90 row_half_mirror row_mask:0xf bank_mask:0xf bound_ctrl:1
	ds_read_b128 v[50:53], v110 offset:19456
	ds_read_b128 v[68:71], v110 offset:15616
	v_add_f32_dpp v92, v90, v90 row_mirror row_mask:0xf bank_mask:0xf bound_ctrl:1
	ds_read_b32 v76, v111 offset:23808
	v_pk_fma_f32 v[2:3], v[92:93], v[64:65], v[82:83] op_sel_hi:[0,1,1] neg_lo:[1,0,0] neg_hi:[1,0,0]
	v_pk_fma_f32 v[4:5], v[92:93], v[66:67], v[84:85] op_sel_hi:[0,1,1] neg_lo:[1,0,0] neg_hi:[1,0,0]
	ds_read_b128 v[64:67], v110 offset:11520
	s_waitcnt lgkmcnt(6)
	v_pk_mul_f32 v[86:87], v[2:3], v[38:39]
	v_pk_mul_f32 v[78:79], v[2:3], v[34:35]
	v_pk_fma_f32 v[86:87], v[4:5], v[40:41], v[86:87]
	v_pk_mul_f32 v[80:81], v[4:5], v[36:37]
	v_pk_mul_f32 v[88:89], v[2:3], v[72:73]
	v_add_f32_e32 v90, v86, v87
	v_pk_fma_f32 v[82:83], v[54:55], v[46:47], v[78:79] op_sel_hi:[0,1,1]
	v_pk_fma_f32 v[88:89], v[4:5], v[74:75], v[88:89]
	v_add_f32_dpp v90, v90, v90 quad_perm:[1,0,3,2] row_mask:0xf bank_mask:0xf bound_ctrl:1
	v_pk_fma_f32 v[84:85], v[54:55], v[48:49], v[80:81] op_sel_hi:[0,1,1]
	ds_read_b128 v[38:41], v110 offset:7680
	v_add_f32_dpp v90, v90, v90 quad_perm:[2,3,0,1] row_mask:0xf bank_mask:0xf bound_ctrl:1
	ds_read_b128 v[34:37], v110 offset:3584
	v_add_f32_e32 v105, v88, v89
	v_add_f32_dpp v90, v90, v90 row_half_mirror row_mask:0xf bank_mask:0xf bound_ctrl:1
	ds_read_b128 v[72:75], v110 offset:19712
	ds_read_b128 v[46:49], v110 offset:15872
	v_add_f32_dpp v92, v90, v90 row_mirror row_mask:0xf bank_mask:0xf bound_ctrl:1
	ds_read_b32 v54, v111 offset:24064
	v_pk_fma_f32 v[2:3], v[92:93], v[42:43], v[82:83] op_sel_hi:[0,1,1] neg_lo:[1,0,0] neg_hi:[1,0,0]
	v_pk_fma_f32 v[4:5], v[92:93], v[44:45], v[84:85] op_sel_hi:[0,1,1] neg_lo:[1,0,0] neg_hi:[1,0,0]
	ds_read_b128 v[42:45], v110 offset:11776
	s_waitcnt lgkmcnt(6)
	v_pk_mul_f32 v[86:87], v[2:3], v[60:61]
	v_pk_mul_f32 v[78:79], v[2:3], v[56:57]
	v_pk_fma_f32 v[86:87], v[4:5], v[62:63], v[86:87]
	v_pk_mul_f32 v[80:81], v[4:5], v[58:59]
	v_pk_mul_f32 v[88:89], v[2:3], v[50:51]
	v_add_f32_e32 v90, v86, v87
	v_pk_fma_f32 v[82:83], v[76:77], v[68:69], v[78:79] op_sel_hi:[0,1,1]
	v_pk_fma_f32 v[88:89], v[4:5], v[52:53], v[88:89]
	v_add_f32_dpp v90, v90, v90 quad_perm:[1,0,3,2] row_mask:0xf bank_mask:0xf bound_ctrl:1
	v_pk_fma_f32 v[84:85], v[76:77], v[70:71], v[80:81] op_sel_hi:[0,1,1]
	ds_read_b128 v[60:63], v110 offset:7936
	v_add_f32_dpp v90, v90, v90 quad_perm:[2,3,0,1] row_mask:0xf bank_mask:0xf bound_ctrl:1
	ds_read_b128 v[56:59], v110 offset:3840
	v_add_f32_e32 v106, v88, v89
	v_add_f32_dpp v90, v90, v90 row_half_mirror row_mask:0xf bank_mask:0xf bound_ctrl:1
	ds_read_b128 v[50:53], v110 offset:19968
	ds_read_b128 v[68:71], v110 offset:16128
	v_add_f32_dpp v92, v90, v90 row_mirror row_mask:0xf bank_mask:0xf bound_ctrl:1
	ds_read_b32 v76, v111 offset:24320
	s_cmpk_eq_i32 s33, 0x10f
	s_cbranch_scc1 .Lscan_tail_last
	v_pk_fma_f32 v[2:3], v[92:93], v[64:65], v[82:83] op_sel_hi:[0,1,1] neg_lo:[1,0,0] neg_hi:[1,0,0]
	v_pk_fma_f32 v[4:5], v[92:93], v[66:67], v[84:85] op_sel_hi:[0,1,1] neg_lo:[1,0,0] neg_hi:[1,0,0]
	ds_read_b128 v[64:67], v110 offset:12032
	s_waitcnt lgkmcnt(6)
	v_pk_mul_f32 v[86:87], v[2:3], v[38:39]
	v_pk_mul_f32 v[78:79], v[2:3], v[34:35]
	v_pk_fma_f32 v[86:87], v[4:5], v[40:41], v[86:87]
	v_pk_mul_f32 v[80:81], v[4:5], v[36:37]
	v_pk_mul_f32 v[88:89], v[2:3], v[72:73]
	v_add_f32_e32 v90, v86, v87
	v_pk_fma_f32 v[82:83], v[54:55], v[46:47], v[78:79] op_sel_hi:[0,1,1]
	v_pk_fma_f32 v[88:89], v[4:5], v[74:75], v[88:89]
	v_add_f32_dpp v90, v90, v90 quad_perm:[1,0,3,2] row_mask:0xf bank_mask:0xf bound_ctrl:1
	v_pk_fma_f32 v[84:85], v[54:55], v[48:49], v[80:81] op_sel_hi:[0,1,1]
	s_waitcnt vmcnt(18)
	v_add_f32_dpp v90, v90, v90 quad_perm:[2,3,0,1] row_mask:0xf bank_mask:0xf bound_ctrl:1
	v_pk_add_f32 v[122:123], v[228:229], -1.0 op_sel_hi:[1,0]
	v_add_f32_e32 v107, v88, v89
	v_add_f32_dpp v90, v90, v90 row_half_mirror row_mask:0xf bank_mask:0xf bound_ctrl:1
	ds_read_b128 v[72:75], v110 offset:20224
	v_pk_add_f32 v[124:125], v[230:231], -1.0 op_sel_hi:[1,0]
	v_add_f32_dpp v92, v90, v90 row_mirror row_mask:0xf bank_mask:0xf bound_ctrl:1
	v_pk_mul_f32 v[118:119], v[232:233], v[228:229]
	v_pk_fma_f32 v[2:3], v[92:93], v[42:43], v[82:83] op_sel_hi:[0,1,1] neg_lo:[1,0,0] neg_hi:[1,0,0]
	v_pk_fma_f32 v[4:5], v[92:93], v[44:45], v[84:85] op_sel_hi:[0,1,1] neg_lo:[1,0,0] neg_hi:[1,0,0]
	v_pk_fma_f32 v[122:123], v[6:7], v[122:123], 1.0 op_sel_hi:[1,1,0]
	s_waitcnt lgkmcnt(1)
	v_pk_mul_f32 v[86:87], v[2:3], v[60:61]
	v_pk_mul_f32 v[78:79], v[2:3], v[56:57]
	v_pk_fma_f32 v[86:87], v[4:5], v[62:63], v[86:87]
	v_pk_mul_f32 v[80:81], v[4:5], v[58:59]
	v_pk_mul_f32 v[88:89], v[2:3], v[50:51]
	v_add_f32_e32 v90, v86, v87
	v_pk_fma_f32 v[82:83], v[76:77], v[68:69], v[78:79] op_sel_hi:[0,1,1]
	v_pk_fma_f32 v[88:89], v[4:5], v[52:53], v[88:89]
	v_add_f32_dpp v90, v90, v90 quad_perm:[1,0,3,2] row_mask:0xf bank_mask:0xf bound_ctrl:1
	v_pk_fma_f32 v[84:85], v[76:77], v[70:71], v[80:81] op_sel_hi:[0,1,1]
	v_pk_fma_f32 v[124:125], v[8:9], v[124:125], 1.0 op_sel_hi:[1,1,0]
	v_add_f32_dpp v90, v90, v90 quad_perm:[2,3,0,1] row_mask:0xf bank_mask:0xf bound_ctrl:1
	v_pk_mul_f32 v[120:121], v[234:235], v[230:231]
	v_add_f32_e32 v108, v88, v89
	v_add_f32_dpp v90, v90, v90 row_half_mirror row_mask:0xf bank_mask:0xf bound_ctrl:1
	v_pk_mul_f32 v[122:123], v[216:217], v[122:123]
	v_pk_mul_f32 v[124:125], v[218:219], v[124:125]
	v_add_f32_dpp v92, v90, v90 row_mirror row_mask:0xf bank_mask:0xf bound_ctrl:1
	ds_write_b128 v112, v[224:227] offset:0
	ds_write_b128 v112, v[232:235] offset:4096
	v_pk_fma_f32 v[2:3], v[92:93], v[64:65], v[82:83] op_sel_hi:[0,1,1] neg_lo:[1,0,0] neg_hi:[1,0,0]
	v_pk_fma_f32 v[4:5], v[92:93], v[66:67], v[84:85] op_sel_hi:[0,1,1] neg_lo:[1,0,0] neg_hi:[1,0,0]
	ds_write_b128 v112, v[212:215] offset:16384
	s_waitcnt lgkmcnt(3)
	v_pk_mul_f32 v[88:89], v[2:3], v[72:73]
	ds_write_b128 v112, v[220:223] offset:20480
	v_pk_fma_f32 v[88:89], v[4:5], v[74:75], v[88:89]
	ds_write_b128 v112, v[118:121] offset:8192
	v_add_f32_e32 v109, v88, v89
	ds_write_b128 v112, v[122:125] offset:12288
	s_waitcnt lgkmcnt(0)
	v_xor_b32_e32 v110, 0x6000, v110
	v_xor_b32_e32 v111, 0x6000, v111
	v_xor_b32_e32 v112, 0x6000, v112
	s_add_i32 s33, s33, 1
	s_barrier
	ds_read_b128 v[38:41], v110 offset:4096
	ds_read_b128 v[34:37], v110 offset:0
	ds_read_b128 v[46:49], v110 offset:12288
	ds_read_b32 v54, v111 offset:20480
	ds_read_b128 v[42:45], v110 offset:8192
	ds_read_b128 v[50:53], v110 offset:16384
	ds_read_b128 v[60:63], v110 offset:4352
	ds_read_b128 v[56:59], v110 offset:256
	ds_read_b128 v[68:71], v110 offset:12544
	ds_read_b32 v76, v111 offset:20736
	ds_read_b128 v[64:67], v110 offset:8448
	ds_read_b128 v[72:75], v110 offset:16640
	s_cmpk_ge_i32 s33, 0x10c
	s_cbranch_scc1 .Lscan_skipload_c3
	v_mul_u32_u24_e32 v0, 0xf00, v113
	v_lshl_add_u32 v125, v113, 10, v115
	v_add_u32_e32 v0, v0, v115
	v_add_u32_e32 v113, s34, v113
	global_load_dwordx4 v[224:227], v125, s[46:47]
	global_load_dwordx4 v[228:231], v125, s[48:49]
	global_load_dwordx4 v[232:235], v125, s[22:23]
	global_load_dwordx4 v[216:219], v0, s[12:13] offset:1024
	global_load_dwordx4 v[212:215], v0, s[12:13]
	global_load_dwordx4 v[220:223], v0, s[12:13] offset:2048
	s_cmp_eq_u32 s33, 11
	s_cbranch_scc0 .Lscan_nogload_c3
	v_mov_b32_e32 v113, v117
	s_branch .Lscan_nogload_c3

.Lscan_nored_c3:
	s_waitcnt lgkmcnt(1)
	v_pk_mul_f32 v[86:87], v[2:3], v[38:39]
	v_pk_mul_f32 v[78:79], v[2:3], v[34:35]
	v_pk_fma_f32 v[86:87], v[4:5], v[40:41], v[86:87]
	v_pk_mul_f32 v[80:81], v[4:5], v[36:37]
	ds_read_b128 v[38:41], v110 offset:4608
	v_add_f32_e32 v90, v86, v87
	v_pk_fma_f32 v[82:83], v[54:55], v[46:47], v[78:79] op_sel_hi:[0,1,1]
	ds_read_b128 v[34:37], v110 offset:512
	v_add_f32_dpp v90, v90, v90 quad_perm:[1,0,3,2] row_mask:0xf bank_mask:0xf bound_ctrl:1
	v_pk_fma_f32 v[84:85], v[54:55], v[48:49], v[80:81] op_sel_hi:[0,1,1]
	ds_read_b128 v[46:49], v110 offset:12800
	v_add_f32_dpp v90, v90, v90 quad_perm:[2,3,0,1] row_mask:0xf bank_mask:0xf bound_ctrl:1
	ds_read_b32 v54, v111 offset:20992
	s_nop 0
	v_add_f32_dpp v90, v90, v90 row_half_mirror row_mask:0xf bank_mask:0xf bound_ctrl:1
	s_nop 0
	s_nop 0
	v_add_f32_dpp v92, v90, v90 row_mirror row_mask:0xf bank_mask:0xf bound_ctrl:1
	v_pk_fma_f32 v[2:3], v[92:93], v[42:43], v[82:83] op_sel_hi:[0,1,1] neg_lo:[1,0,0] neg_hi:[1,0,0]
	v_pk_fma_f32 v[4:5], v[92:93], v[44:45], v[84:85] op_sel_hi:[0,1,1] neg_lo:[1,0,0] neg_hi:[1,0,0]
	ds_read_b128 v[42:45], v110 offset:8704
	v_pk_mul_f32 v[86:87], v[2:3], v[60:61]
	v_pk_mul_f32 v[78:79], v[2:3], v[56:57]
	v_pk_fma_f32 v[86:87], v[4:5], v[62:63], v[86:87]
	v_pk_mul_f32 v[80:81], v[4:5], v[58:59]
	v_pk_mul_f32 v[88:89], v[2:3], v[50:51]
	v_add_f32_e32 v90, v86, v87
	v_pk_fma_f32 v[82:83], v[76:77], v[68:69], v[78:79] op_sel_hi:[0,1,1]
	v_pk_fma_f32 v[88:89], v[4:5], v[52:53], v[88:89]
	v_add_f32_dpp v90, v90, v90 quad_perm:[1,0,3,2] row_mask:0xf bank_mask:0xf bound_ctrl:1
	v_pk_fma_f32 v[84:85], v[76:77], v[70:71], v[80:81] op_sel_hi:[0,1,1]
	ds_read_b128 v[60:63], v110 offset:4864
	v_add_f32_dpp v90, v90, v90 quad_perm:[2,3,0,1] row_mask:0xf bank_mask:0xf bound_ctrl:1
	ds_read_b128 v[56:59], v110 offset:768
	v_add_f32_e32 v94, v88, v89
	v_add_f32_dpp v90, v90, v90 row_half_mirror row_mask:0xf bank_mask:0xf bound_ctrl:1
	ds_read_b128 v[50:53], v110 offset:16896
	ds_read_b128 v[68:71], v110 offset:13056
	v_add_f32_dpp v92, v90, v90 row_mirror row_mask:0xf bank_mask:0xf bound_ctrl:1
	ds_read_b32 v76, v111 offset:21248
	v_pk_fma_f32 v[2:3], v[92:93], v[64:65], v[82:83] op_sel_hi:[0,1,1] neg_lo:[1,0,0] neg_hi:[1,0,0]
	v_pk_fma_f32 v[4:5], v[92:93], v[66:67], v[84:85] op_sel_hi:[0,1,1] neg_lo:[1,0,0] neg_hi:[1,0,0]
	ds_read_b128 v[64:67], v110 offset:8960
	s_waitcnt lgkmcnt(6)
	v_pk_mul_f32 v[86:87], v[2:3], v[38:39]
	v_pk_mul_f32 v[78:79], v[2:3], v[34:35]
	v_pk_fma_f32 v[86:87], v[4:5], v[40:41], v[86:87]
	v_pk_mul_f32 v[80:81], v[4:5], v[36:37]
	v_pk_mul_f32 v[88:89], v[2:3], v[72:73]
	v_add_f32_e32 v90, v86, v87
	v_pk_fma_f32 v[82:83], v[54:55], v[46:47], v[78:79] op_sel_hi:[0,1,1]
	v_pk_fma_f32 v[88:89], v[4:5], v[74:75], v[88:89]
	v_add_f32_dpp v90, v90, v90 quad_perm:[1,0,3,2] row_mask:0xf bank_mask:0xf bound_ctrl:1
	v_pk_fma_f32 v[84:85], v[54:55], v[48:49], v[80:81] op_sel_hi:[0,1,1]
	ds_read_b128 v[38:41], v110 offset:5120
	v_add_f32_dpp v90, v90, v90 quad_perm:[2,3,0,1] row_mask:0xf bank_mask:0xf bound_ctrl:1
	ds_read_b128 v[34:37], v110 offset:1024
	v_add_f32_e32 v95, v88, v89
	v_add_f32_dpp v90, v90, v90 row_half_mirror row_mask:0xf bank_mask:0xf bound_ctrl:1
	ds_read_b128 v[72:75], v110 offset:17152
	ds_read_b128 v[46:49], v110 offset:13312
	v_add_f32_dpp v92, v90, v90 row_mirror row_mask:0xf bank_mask:0xf bound_ctrl:1
	ds_read_b32 v54, v111 offset:21504
	v_pk_fma_f32 v[2:3], v[92:93], v[42:43], v[82:83] op_sel_hi:[0,1,1] neg_lo:[1,0,0] neg_hi:[1,0,0]
	v_pk_fma_f32 v[4:5], v[92:93], v[44:45], v[84:85] op_sel_hi:[0,1,1] neg_lo:[1,0,0] neg_hi:[1,0,0]
	ds_read_b128 v[42:45], v110 offset:9216
	s_waitcnt lgkmcnt(6)
	v_pk_mul_f32 v[86:87], v[2:3], v[60:61]
	v_pk_mul_f32 v[78:79], v[2:3], v[56:57]
	v_pk_fma_f32 v[86:87], v[4:5], v[62:63], v[86:87]
	v_pk_mul_f32 v[80:81], v[4:5], v[58:59]
	v_pk_mul_f32 v[88:89], v[2:3], v[50:51]
	v_add_f32_e32 v90, v86, v87
	v_pk_fma_f32 v[82:83], v[76:77], v[68:69], v[78:79] op_sel_hi:[0,1,1]
	v_pk_fma_f32 v[88:89], v[4:5], v[52:53], v[88:89]
	v_add_f32_dpp v90, v90, v90 quad_perm:[1,0,3,2] row_mask:0xf bank_mask:0xf bound_ctrl:1
	v_pk_fma_f32 v[84:85], v[76:77], v[70:71], v[80:81] op_sel_hi:[0,1,1]
	ds_read_b128 v[60:63], v110 offset:5376
	v_add_f32_dpp v90, v90, v90 quad_perm:[2,3,0,1] row_mask:0xf bank_mask:0xf bound_ctrl:1
	ds_read_b128 v[56:59], v110 offset:1280
	v_add_f32_e32 v96, v88, v89
	v_add_f32_dpp v90, v90, v90 row_half_mirror row_mask:0xf bank_mask:0xf bound_ctrl:1
	ds_read_b128 v[50:53], v110 offset:17408
	ds_read_b128 v[68:71], v110 offset:13568
	v_add_f32_dpp v92, v90, v90 row_mirror row_mask:0xf bank_mask:0xf bound_ctrl:1
	ds_read_b32 v76, v111 offset:21760
	v_pk_fma_f32 v[2:3], v[92:93], v[64:65], v[82:83] op_sel_hi:[0,1,1] neg_lo:[1,0,0] neg_hi:[1,0,0]
	v_pk_fma_f32 v[4:5], v[92:93], v[66:67], v[84:85] op_sel_hi:[0,1,1] neg_lo:[1,0,0] neg_hi:[1,0,0]
	ds_read_b128 v[64:67], v110 offset:9472
	s_waitcnt lgkmcnt(6)
	v_pk_mul_f32 v[86:87], v[2:3], v[38:39]
	v_pk_mul_f32 v[78:79], v[2:3], v[34:35]
	v_pk_fma_f32 v[86:87], v[4:5], v[40:41], v[86:87]
	v_pk_mul_f32 v[80:81], v[4:5], v[36:37]
	v_pk_mul_f32 v[88:89], v[2:3], v[72:73]
	v_add_f32_e32 v90, v86, v87
	v_pk_fma_f32 v[82:83], v[54:55], v[46:47], v[78:79] op_sel_hi:[0,1,1]
	v_pk_fma_f32 v[88:89], v[4:5], v[74:75], v[88:89]
	v_add_f32_dpp v90, v90, v90 quad_perm:[1,0,3,2] row_mask:0xf bank_mask:0xf bound_ctrl:1
	v_pk_fma_f32 v[84:85], v[54:55], v[48:49], v[80:81] op_sel_hi:[0,1,1]
	ds_read_b128 v[38:41], v110 offset:5632
	v_add_f32_dpp v90, v90, v90 quad_perm:[2,3,0,1] row_mask:0xf bank_mask:0xf bound_ctrl:1
	ds_read_b128 v[34:37], v110 offset:1536
	v_add_f32_e32 v97, v88, v89
	v_add_f32_dpp v90, v90, v90 row_half_mirror row_mask:0xf bank_mask:0xf bound_ctrl:1
	ds_read_b128 v[72:75], v110 offset:17664
	ds_read_b128 v[46:49], v110 offset:13824
	v_add_f32_dpp v92, v90, v90 row_mirror row_mask:0xf bank_mask:0xf bound_ctrl:1
	ds_read_b32 v54, v111 offset:22016
	v_pk_fma_f32 v[2:3], v[92:93], v[42:43], v[82:83] op_sel_hi:[0,1,1] neg_lo:[1,0,0] neg_hi:[1,0,0]
	v_pk_fma_f32 v[4:5], v[92:93], v[44:45], v[84:85] op_sel_hi:[0,1,1] neg_lo:[1,0,0] neg_hi:[1,0,0]
	ds_read_b128 v[42:45], v110 offset:9728
	s_waitcnt lgkmcnt(6)
	v_pk_mul_f32 v[86:87], v[2:3], v[60:61]
	v_pk_mul_f32 v[78:79], v[2:3], v[56:57]
	v_pk_fma_f32 v[86:87], v[4:5], v[62:63], v[86:87]
	v_pk_mul_f32 v[80:81], v[4:5], v[58:59]
	v_pk_mul_f32 v[88:89], v[2:3], v[50:51]
	v_add_f32_e32 v90, v86, v87
	v_pk_fma_f32 v[82:83], v[76:77], v[68:69], v[78:79] op_sel_hi:[0,1,1]
	v_pk_fma_f32 v[88:89], v[4:5], v[52:53], v[88:89]
	v_add_f32_dpp v90, v90, v90 quad_perm:[1,0,3,2] row_mask:0xf bank_mask:0xf bound_ctrl:1
	v_pk_fma_f32 v[84:85], v[76:77], v[70:71], v[80:81] op_sel_hi:[0,1,1]
	ds_read_b128 v[60:63], v110 offset:5888
	v_add_f32_dpp v90, v90, v90 quad_perm:[2,3,0,1] row_mask:0xf bank_mask:0xf bound_ctrl:1
	ds_read_b128 v[56:59], v110 offset:1792
	v_add_f32_e32 v98, v88, v89
	v_add_f32_dpp v90, v90, v90 row_half_mirror row_mask:0xf bank_mask:0xf bound_ctrl:1
	ds_read_b128 v[50:53], v110 offset:17920
	ds_read_b128 v[68:71], v110 offset:14080
	v_add_f32_dpp v92, v90, v90 row_mirror row_mask:0xf bank_mask:0xf bound_ctrl:1
	ds_read_b32 v76, v111 offset:22272
	v_pk_fma_f32 v[2:3], v[92:93], v[64:65], v[82:83] op_sel_hi:[0,1,1] neg_lo:[1,0,0] neg_hi:[1,0,0]
	v_pk_fma_f32 v[4:5], v[92:93], v[66:67], v[84:85] op_sel_hi:[0,1,1] neg_lo:[1,0,0] neg_hi:[1,0,0]
	ds_read_b128 v[64:67], v110 offset:9984
	s_waitcnt lgkmcnt(6)
	v_pk_mul_f32 v[86:87], v[2:3], v[38:39]
	v_pk_mul_f32 v[78:79], v[2:3], v[34:35]
	v_pk_fma_f32 v[86:87], v[4:5], v[40:41], v[86:87]
	v_pk_mul_f32 v[80:81], v[4:5], v[36:37]
	v_pk_mul_f32 v[88:89], v[2:3], v[72:73]
	v_add_f32_e32 v90, v86, v87
	v_pk_fma_f32 v[82:83], v[54:55], v[46:47], v[78:79] op_sel_hi:[0,1,1]
	v_pk_fma_f32 v[88:89], v[4:5], v[74:75], v[88:89]
	v_add_f32_dpp v90, v90, v90 quad_perm:[1,0,3,2] row_mask:0xf bank_mask:0xf bound_ctrl:1
	v_pk_fma_f32 v[84:85], v[54:55], v[48:49], v[80:81] op_sel_hi:[0,1,1]
	ds_read_b128 v[38:41], v110 offset:6144
	v_add_f32_dpp v90, v90, v90 quad_perm:[2,3,0,1] row_mask:0xf bank_mask:0xf bound_ctrl:1
	ds_read_b128 v[34:37], v110 offset:2048
	v_add_f32_e32 v99, v88, v89
	v_add_f32_dpp v90, v90, v90 row_half_mirror row_mask:0xf bank_mask:0xf bound_ctrl:1
	ds_read_b128 v[72:75], v110 offset:18176
	ds_read_b128 v[46:49], v110 offset:14336
	v_add_f32_dpp v92, v90, v90 row_mirror row_mask:0xf bank_mask:0xf bound_ctrl:1
	ds_read_b32 v54, v111 offset:22528
	v_pk_fma_f32 v[2:3], v[92:93], v[42:43], v[82:83] op_sel_hi:[0,1,1] neg_lo:[1,0,0] neg_hi:[1,0,0]
	v_pk_fma_f32 v[4:5], v[92:93], v[44:45], v[84:85] op_sel_hi:[0,1,1] neg_lo:[1,0,0] neg_hi:[1,0,0]
	ds_read_b128 v[42:45], v110 offset:10240
	s_waitcnt lgkmcnt(6)
	v_pk_mul_f32 v[86:87], v[2:3], v[60:61]
	v_pk_mul_f32 v[78:79], v[2:3], v[56:57]
	v_pk_fma_f32 v[86:87], v[4:5], v[62:63], v[86:87]
	v_pk_mul_f32 v[80:81], v[4:5], v[58:59]
	v_pk_mul_f32 v[88:89], v[2:3], v[50:51]
	v_add_f32_e32 v90, v86, v87
	v_pk_fma_f32 v[82:83], v[76:77], v[68:69], v[78:79] op_sel_hi:[0,1,1]
	v_pk_fma_f32 v[88:89], v[4:5], v[52:53], v[88:89]
	v_add_f32_dpp v90, v90, v90 quad_perm:[1,0,3,2] row_mask:0xf bank_mask:0xf bound_ctrl:1
	v_pk_fma_f32 v[84:85], v[76:77], v[70:71], v[80:81] op_sel_hi:[0,1,1]
	ds_read_b128 v[60:63], v110 offset:6400
	v_add_f32_dpp v90, v90, v90 quad_perm:[2,3,0,1] row_mask:0xf bank_mask:0xf bound_ctrl:1
	ds_read_b128 v[56:59], v110 offset:2304
	v_add_f32_e32 v100, v88, v89
	v_add_f32_dpp v90, v90, v90 row_half_mirror row_mask:0xf bank_mask:0xf bound_ctrl:1
	ds_read_b128 v[50:53], v110 offset:18432
	ds_read_b128 v[68:71], v110 offset:14592
	v_add_f32_dpp v92, v90, v90 row_mirror row_mask:0xf bank_mask:0xf bound_ctrl:1
	ds_read_b32 v76, v111 offset:22784
	v_pk_fma_f32 v[2:3], v[92:93], v[64:65], v[82:83] op_sel_hi:[0,1,1] neg_lo:[1,0,0] neg_hi:[1,0,0]
	v_pk_fma_f32 v[4:5], v[92:93], v[66:67], v[84:85] op_sel_hi:[0,1,1] neg_lo:[1,0,0] neg_hi:[1,0,0]
	ds_read_b128 v[64:67], v110 offset:10496
	s_waitcnt lgkmcnt(6)
	v_pk_mul_f32 v[86:87], v[2:3], v[38:39]
	v_pk_mul_f32 v[78:79], v[2:3], v[34:35]
	v_pk_fma_f32 v[86:87], v[4:5], v[40:41], v[86:87]
	v_pk_mul_f32 v[80:81], v[4:5], v[36:37]
	v_pk_mul_f32 v[88:89], v[2:3], v[72:73]
	v_add_f32_e32 v90, v86, v87
	v_pk_fma_f32 v[82:83], v[54:55], v[46:47], v[78:79] op_sel_hi:[0,1,1]
	v_pk_fma_f32 v[88:89], v[4:5], v[74:75], v[88:89]
	v_add_f32_dpp v90, v90, v90 quad_perm:[1,0,3,2] row_mask:0xf bank_mask:0xf bound_ctrl:1
	v_pk_fma_f32 v[84:85], v[54:55], v[48:49], v[80:81] op_sel_hi:[0,1,1]
	ds_read_b128 v[38:41], v110 offset:6656
	v_add_f32_dpp v90, v90, v90 quad_perm:[2,3,0,1] row_mask:0xf bank_mask:0xf bound_ctrl:1
	ds_read_b128 v[34:37], v110 offset:2560
	v_add_f32_e32 v101, v88, v89
	v_add_f32_dpp v90, v90, v90 row_half_mirror row_mask:0xf bank_mask:0xf bound_ctrl:1
	ds_read_b128 v[72:75], v110 offset:18688
	ds_read_b128 v[46:49], v110 offset:14848
	v_add_f32_dpp v92, v90, v90 row_mirror row_mask:0xf bank_mask:0xf bound_ctrl:1
	ds_read_b32 v54, v111 offset:23040
	v_pk_fma_f32 v[2:3], v[92:93], v[42:43], v[82:83] op_sel_hi:[0,1,1] neg_lo:[1,0,0] neg_hi:[1,0,0]
	v_pk_fma_f32 v[4:5], v[92:93], v[44:45], v[84:85] op_sel_hi:[0,1,1] neg_lo:[1,0,0] neg_hi:[1,0,0]
	ds_read_b128 v[42:45], v110 offset:10752
	s_waitcnt lgkmcnt(6)
	v_pk_mul_f32 v[86:87], v[2:3], v[60:61]
	v_pk_mul_f32 v[78:79], v[2:3], v[56:57]
	v_pk_fma_f32 v[86:87], v[4:5], v[62:63], v[86:87]
	v_pk_mul_f32 v[80:81], v[4:5], v[58:59]
	v_pk_mul_f32 v[88:89], v[2:3], v[50:51]
	v_add_f32_e32 v90, v86, v87
	v_pk_fma_f32 v[82:83], v[76:77], v[68:69], v[78:79] op_sel_hi:[0,1,1]
	v_pk_fma_f32 v[88:89], v[4:5], v[52:53], v[88:89]
	v_add_f32_dpp v90, v90, v90 quad_perm:[1,0,3,2] row_mask:0xf bank_mask:0xf bound_ctrl:1
	v_pk_fma_f32 v[84:85], v[76:77], v[70:71], v[80:81] op_sel_hi:[0,1,1]
	ds_read_b128 v[60:63], v110 offset:6912
	v_add_f32_dpp v90, v90, v90 quad_perm:[2,3,0,1] row_mask:0xf bank_mask:0xf bound_ctrl:1
	ds_read_b128 v[56:59], v110 offset:2816
	v_add_f32_e32 v102, v88, v89
	v_add_f32_dpp v90, v90, v90 row_half_mirror row_mask:0xf bank_mask:0xf bound_ctrl:1
	ds_read_b128 v[50:53], v110 offset:18944
	ds_read_b128 v[68:71], v110 offset:15104
	v_add_f32_dpp v92, v90, v90 row_mirror row_mask:0xf bank_mask:0xf bound_ctrl:1
	ds_read_b32 v76, v111 offset:23296
	v_pk_fma_f32 v[2:3], v[92:93], v[64:65], v[82:83] op_sel_hi:[0,1,1] neg_lo:[1,0,0] neg_hi:[1,0,0]
	v_pk_fma_f32 v[4:5], v[92:93], v[66:67], v[84:85] op_sel_hi:[0,1,1] neg_lo:[1,0,0] neg_hi:[1,0,0]
	ds_read_b128 v[64:67], v110 offset:11008
	s_waitcnt lgkmcnt(6)
	v_pk_mul_f32 v[86:87], v[2:3], v[38:39]
	v_pk_mul_f32 v[78:79], v[2:3], v[34:35]
	v_pk_fma_f32 v[86:87], v[4:5], v[40:41], v[86:87]
	v_pk_mul_f32 v[80:81], v[4:5], v[36:37]
	v_pk_mul_f32 v[88:89], v[2:3], v[72:73]
	v_add_f32_e32 v90, v86, v87
	v_pk_fma_f32 v[82:83], v[54:55], v[46:47], v[78:79] op_sel_hi:[0,1,1]
	v_pk_fma_f32 v[88:89], v[4:5], v[74:75], v[88:89]
	v_add_f32_dpp v90, v90, v90 quad_perm:[1,0,3,2] row_mask:0xf bank_mask:0xf bound_ctrl:1
	v_pk_fma_f32 v[84:85], v[54:55], v[48:49], v[80:81] op_sel_hi:[0,1,1]
	ds_read_b128 v[38:41], v110 offset:7168
	v_add_f32_dpp v90, v90, v90 quad_perm:[2,3,0,1] row_mask:0xf bank_mask:0xf bound_ctrl:1
	ds_read_b128 v[34:37], v110 offset:3072
	v_add_f32_e32 v103, v88, v89
	v_add_f32_dpp v90, v90, v90 row_half_mirror row_mask:0xf bank_mask:0xf bound_ctrl:1
	ds_read_b128 v[72:75], v110 offset:19200
	ds_read_b128 v[46:49], v110 offset:15360
	v_add_f32_dpp v92, v90, v90 row_mirror row_mask:0xf bank_mask:0xf bound_ctrl:1
	ds_read_b32 v54, v111 offset:23552
	v_pk_fma_f32 v[2:3], v[92:93], v[42:43], v[82:83] op_sel_hi:[0,1,1] neg_lo:[1,0,0] neg_hi:[1,0,0]
	v_pk_fma_f32 v[4:5], v[92:93], v[44:45], v[84:85] op_sel_hi:[0,1,1] neg_lo:[1,0,0] neg_hi:[1,0,0]
	ds_read_b128 v[42:45], v110 offset:11264
	s_waitcnt lgkmcnt(6)
	v_pk_mul_f32 v[86:87], v[2:3], v[60:61]
	v_pk_mul_f32 v[78:79], v[2:3], v[56:57]
	v_pk_fma_f32 v[86:87], v[4:5], v[62:63], v[86:87]
	v_pk_mul_f32 v[80:81], v[4:5], v[58:59]
	v_pk_mul_f32 v[88:89], v[2:3], v[50:51]
	v_add_f32_e32 v90, v86, v87
	v_pk_fma_f32 v[82:83], v[76:77], v[68:69], v[78:79] op_sel_hi:[0,1,1]
	v_pk_fma_f32 v[88:89], v[4:5], v[52:53], v[88:89]
	v_add_f32_dpp v90, v90, v90 quad_perm:[1,0,3,2] row_mask:0xf bank_mask:0xf bound_ctrl:1
	v_pk_fma_f32 v[84:85], v[76:77], v[70:71], v[80:81] op_sel_hi:[0,1,1]
	ds_read_b128 v[60:63], v110 offset:7424
	v_add_f32_dpp v90, v90, v90 quad_perm:[2,3,0,1] row_mask:0xf bank_mask:0xf bound_ctrl:1
	ds_read_b128 v[56:59], v110 offset:3328
	v_add_f32_e32 v104, v88, v89
	v_add_f32_dpp v90, v90, v90 row_half_mirror row_mask:0xf bank_mask:0xf bound_ctrl:1
	ds_read_b128 v[50:53], v110 offset:19456
	ds_read_b128 v[68:71], v110 offset:15616
	v_add_f32_dpp v92, v90, v90 row_mirror row_mask:0xf bank_mask:0xf bound_ctrl:1
	ds_read_b32 v76, v111 offset:23808
	v_pk_fma_f32 v[2:3], v[92:93], v[64:65], v[82:83] op_sel_hi:[0,1,1] neg_lo:[1,0,0] neg_hi:[1,0,0]
	v_pk_fma_f32 v[4:5], v[92:93], v[66:67], v[84:85] op_sel_hi:[0,1,1] neg_lo:[1,0,0] neg_hi:[1,0,0]
	ds_read_b128 v[64:67], v110 offset:11520
	s_waitcnt lgkmcnt(6)
	v_pk_mul_f32 v[86:87], v[2:3], v[38:39]
	v_pk_mul_f32 v[78:79], v[2:3], v[34:35]
	v_pk_fma_f32 v[86:87], v[4:5], v[40:41], v[86:87]
	v_pk_mul_f32 v[80:81], v[4:5], v[36:37]
	v_pk_mul_f32 v[88:89], v[2:3], v[72:73]
	v_add_f32_e32 v90, v86, v87
	v_pk_fma_f32 v[82:83], v[54:55], v[46:47], v[78:79] op_sel_hi:[0,1,1]
	v_pk_fma_f32 v[88:89], v[4:5], v[74:75], v[88:89]
	v_add_f32_dpp v90, v90, v90 quad_perm:[1,0,3,2] row_mask:0xf bank_mask:0xf bound_ctrl:1
	v_pk_fma_f32 v[84:85], v[54:55], v[48:49], v[80:81] op_sel_hi:[0,1,1]
	ds_read_b128 v[38:41], v110 offset:7680
	v_add_f32_dpp v90, v90, v90 quad_perm:[2,3,0,1] row_mask:0xf bank_mask:0xf bound_ctrl:1
	ds_read_b128 v[34:37], v110 offset:3584
	v_add_f32_e32 v105, v88, v89
	v_add_f32_dpp v90, v90, v90 row_half_mirror row_mask:0xf bank_mask:0xf bound_ctrl:1
	ds_read_b128 v[72:75], v110 offset:19712
	ds_read_b128 v[46:49], v110 offset:15872
	v_add_f32_dpp v92, v90, v90 row_mirror row_mask:0xf bank_mask:0xf bound_ctrl:1
	ds_read_b32 v54, v111 offset:24064
	v_pk_fma_f32 v[2:3], v[92:93], v[42:43], v[82:83] op_sel_hi:[0,1,1] neg_lo:[1,0,0] neg_hi:[1,0,0]
	v_pk_fma_f32 v[4:5], v[92:93], v[44:45], v[84:85] op_sel_hi:[0,1,1] neg_lo:[1,0,0] neg_hi:[1,0,0]
	ds_read_b128 v[42:45], v110 offset:11776
	s_waitcnt lgkmcnt(6)
	v_pk_mul_f32 v[86:87], v[2:3], v[60:61]
	v_pk_mul_f32 v[78:79], v[2:3], v[56:57]
	v_pk_fma_f32 v[86:87], v[4:5], v[62:63], v[86:87]
	v_pk_mul_f32 v[80:81], v[4:5], v[58:59]
	v_pk_mul_f32 v[88:89], v[2:3], v[50:51]
	v_add_f32_e32 v90, v86, v87
	v_pk_fma_f32 v[82:83], v[76:77], v[68:69], v[78:79] op_sel_hi:[0,1,1]
	v_pk_fma_f32 v[88:89], v[4:5], v[52:53], v[88:89]
	v_add_f32_dpp v90, v90, v90 quad_perm:[1,0,3,2] row_mask:0xf bank_mask:0xf bound_ctrl:1
	v_pk_fma_f32 v[84:85], v[76:77], v[70:71], v[80:81] op_sel_hi:[0,1,1]
	ds_read_b128 v[60:63], v110 offset:7936
	v_add_f32_dpp v90, v90, v90 quad_perm:[2,3,0,1] row_mask:0xf bank_mask:0xf bound_ctrl:1
	ds_read_b128 v[56:59], v110 offset:3840
	v_add_f32_e32 v106, v88, v89
	v_add_f32_dpp v90, v90, v90 row_half_mirror row_mask:0xf bank_mask:0xf bound_ctrl:1
	ds_read_b128 v[50:53], v110 offset:19968
	ds_read_b128 v[68:71], v110 offset:16128
	v_add_f32_dpp v92, v90, v90 row_mirror row_mask:0xf bank_mask:0xf bound_ctrl:1
	ds_read_b32 v76, v111 offset:24320
	s_cmpk_eq_i32 s33, 0x10f
	s_cbranch_scc1 .Lscan_tail_last
	v_pk_fma_f32 v[2:3], v[92:93], v[64:65], v[82:83] op_sel_hi:[0,1,1] neg_lo:[1,0,0] neg_hi:[1,0,0]
	v_pk_fma_f32 v[4:5], v[92:93], v[66:67], v[84:85] op_sel_hi:[0,1,1] neg_lo:[1,0,0] neg_hi:[1,0,0]
	ds_read_b128 v[64:67], v110 offset:12032
	s_waitcnt lgkmcnt(6)
	v_pk_mul_f32 v[86:87], v[2:3], v[38:39]
	v_pk_mul_f32 v[78:79], v[2:3], v[34:35]
	v_pk_fma_f32 v[86:87], v[4:5], v[40:41], v[86:87]
	v_pk_mul_f32 v[80:81], v[4:5], v[36:37]
	v_pk_mul_f32 v[88:89], v[2:3], v[72:73]
	v_add_f32_e32 v90, v86, v87
	v_pk_fma_f32 v[82:83], v[54:55], v[46:47], v[78:79] op_sel_hi:[0,1,1]
	v_pk_fma_f32 v[88:89], v[4:5], v[74:75], v[88:89]
	v_add_f32_dpp v90, v90, v90 quad_perm:[1,0,3,2] row_mask:0xf bank_mask:0xf bound_ctrl:1
	v_pk_fma_f32 v[84:85], v[54:55], v[48:49], v[80:81] op_sel_hi:[0,1,1]
	s_waitcnt vmcnt(18)
	v_add_f32_dpp v90, v90, v90 quad_perm:[2,3,0,1] row_mask:0xf bank_mask:0xf bound_ctrl:1
	v_pk_add_f32 v[122:123], v[26:27], -1.0 op_sel_hi:[1,0]
	v_add_f32_e32 v107, v88, v89
	v_add_f32_dpp v90, v90, v90 row_half_mirror row_mask:0xf bank_mask:0xf bound_ctrl:1
	ds_read_b128 v[72:75], v110 offset:20224
	v_pk_add_f32 v[124:125], v[28:29], -1.0 op_sel_hi:[1,0]
	v_add_f32_dpp v92, v90, v90 row_mirror row_mask:0xf bank_mask:0xf bound_ctrl:1
	v_pk_mul_f32 v[118:119], v[30:31], v[26:27]
	v_pk_fma_f32 v[2:3], v[92:93], v[42:43], v[82:83] op_sel_hi:[0,1,1] neg_lo:[1,0,0] neg_hi:[1,0,0]
	v_pk_fma_f32 v[4:5], v[92:93], v[44:45], v[84:85] op_sel_hi:[0,1,1] neg_lo:[1,0,0] neg_hi:[1,0,0]
	v_pk_fma_f32 v[122:123], v[6:7], v[122:123], 1.0 op_sel_hi:[1,1,0]
	s_waitcnt lgkmcnt(1)
	v_pk_mul_f32 v[86:87], v[2:3], v[60:61]
	v_pk_mul_f32 v[78:79], v[2:3], v[56:57]
	v_pk_fma_f32 v[86:87], v[4:5], v[62:63], v[86:87]
	v_pk_mul_f32 v[80:81], v[4:5], v[58:59]
	v_pk_mul_f32 v[88:89], v[2:3], v[50:51]
	v_add_f32_e32 v90, v86, v87
	v_pk_fma_f32 v[82:83], v[76:77], v[68:69], v[78:79] op_sel_hi:[0,1,1]
	v_pk_fma_f32 v[88:89], v[4:5], v[52:53], v[88:89]
	v_add_f32_dpp v90, v90, v90 quad_perm:[1,0,3,2] row_mask:0xf bank_mask:0xf bound_ctrl:1
	v_pk_fma_f32 v[84:85], v[76:77], v[70:71], v[80:81] op_sel_hi:[0,1,1]
	v_pk_fma_f32 v[124:125], v[8:9], v[124:125], 1.0 op_sel_hi:[1,1,0]
	v_add_f32_dpp v90, v90, v90 quad_perm:[2,3,0,1] row_mask:0xf bank_mask:0xf bound_ctrl:1
	v_pk_mul_f32 v[120:121], v[32:33], v[28:29]
	v_add_f32_e32 v108, v88, v89
	v_add_f32_dpp v90, v90, v90 row_half_mirror row_mask:0xf bank_mask:0xf bound_ctrl:1
	v_pk_mul_f32 v[122:123], v[14:15], v[122:123]
	v_pk_mul_f32 v[124:125], v[16:17], v[124:125]
	v_add_f32_dpp v92, v90, v90 row_mirror row_mask:0xf bank_mask:0xf bound_ctrl:1
	ds_write_b128 v112, v[22:25] offset:0
	ds_write_b128 v112, v[30:33] offset:4096
	v_pk_fma_f32 v[2:3], v[92:93], v[64:65], v[82:83] op_sel_hi:[0,1,1] neg_lo:[1,0,0] neg_hi:[1,0,0]
	v_pk_fma_f32 v[4:5], v[92:93], v[66:67], v[84:85] op_sel_hi:[0,1,1] neg_lo:[1,0,0] neg_hi:[1,0,0]
	ds_write_b128 v112, v[10:13] offset:16384
	s_waitcnt lgkmcnt(3)
	v_pk_mul_f32 v[88:89], v[2:3], v[72:73]
	ds_write_b128 v112, v[18:21] offset:20480
	v_pk_fma_f32 v[88:89], v[4:5], v[74:75], v[88:89]
	ds_write_b128 v112, v[118:121] offset:8192
	v_add_f32_e32 v109, v88, v89
	ds_write_b128 v112, v[122:125] offset:12288
	s_waitcnt lgkmcnt(0)
	v_xor_b32_e32 v110, 0x6000, v110
	v_xor_b32_e32 v111, 0x6000, v111
	v_xor_b32_e32 v112, 0x6000, v112
	s_add_i32 s33, s33, 1
	s_barrier
	s_branch .Lscan_chunk
